# P9 conv epilogue: removed 256 dead DPP destination inits (hazards re-padded)
# speedup vs baseline: 1.0522x; 1.0062x over previous
;     __device__ __forceinline__ bool next(int i, Unit& u) const { return decode(i * G + c, u); }
; template <class Epi, class Sched, bool DEFER>
; __device__ __forceinline__ void gemm_fast_core(LAS unsigned char* lds, const GemmP g, const Sched& S, const Epi& E, f32x4 (&acc)[2][2][4][2], Unit& cur) {
;     ...
;     for (;;) {
;         const bool has_next = S.next(ui + 1, nxt);
;         const char* nA = has_next ? (const char*)g.aptr(nxt) : cA; const char* nB = has_next ? (const char*)g.bptr(nxt) : cB;
;         for (int t = 0; t < nt; t += 2) {
;             const bool last = (t == nt - 2);
;             const char* a1 = cA + (size_t)(t + 1) * kstep;
;             const char* a2 = last ? nA : cA + (size_t)(t + 2) * kstep; const char* b2 = last ? nB : cB + (size_t)(t + 2) * kstep;
;     ...
;         for (int a = 0; a < 2; ++a)
; #pragma unroll
;             for (int b = 0; b < 2; ++b)
; #pragma unroll
;                 for (int m = 0; m < 4; ++m)
; #pragma unroll
;                     for (int n = 0; n < 2; ++n) acc[a][b][m][n] = (f32x4){0.f, 0.f, 0.f, 0.f};
.LBB0_235:
	s_ashr_i32 s25, s24, 31
	s_lshl_b64 s[30:31], s[24:25], 20
	s_add_u32 s30, s90, s30
	s_addc_u32 s31, s91, s31
	s_and_b64 s[34:35], s[28:29], exec
	s_cselect_b32 s3, s31, s37
	s_cselect_b32 s25, s30, s36
	s_ashr_i32 s23, s22, 31
	s_lshl_b64 s[34:35], s[22:23], 20
	s_add_u32 s34, s10, s34
	s_addc_u32 s35, s11, s35
	s_and_b64 s[40:41], s[28:29], exec
	s_cselect_b32 s23, s35, s39
	s_cselect_b32 s27, s34, s38
	s_add_u32 s36, s36, 0x80080
	s_addc_u32 s37, s37, 0
	s_add_u32 s33, s38, 0x100
	v_mov_b32_e32 v0, 0
	s_addc_u32 s42, s39, 0
	s_mov_b32 s43, -2
	v_mov_b32_e32 v1, v0
	v_mov_b32_e32 v2, v0
	v_mov_b32_e32 v3, v0
	v_mov_b32_e32 v4, v0
	v_mov_b32_e32 v5, v0
	v_mov_b32_e32 v6, v0
	v_mov_b32_e32 v7, v0
	v_mov_b32_e32 v16, v0
	v_mov_b32_e32 v17, v0
	v_mov_b32_e32 v18, v0
	v_mov_b32_e32 v19, v0
	v_mov_b32_e32 v20, v0
	v_mov_b32_e32 v21, v0
	v_mov_b32_e32 v22, v0
	v_mov_b32_e32 v23, v0
	v_mov_b32_e32 v32, v0
	v_mov_b32_e32 v33, v0
	v_mov_b32_e32 v34, v0
	v_mov_b32_e32 v35, v0
	v_mov_b32_e32 v36, v0
	v_mov_b32_e32 v37, v0
	v_mov_b32_e32 v38, v0
	v_mov_b32_e32 v39, v0
	v_mov_b32_e32 v48, v0
	v_mov_b32_e32 v49, v0
	v_mov_b32_e32 v50, v0
	v_mov_b32_e32 v51, v0
	v_mov_b32_e32 v52, v0
	v_mov_b32_e32 v53, v0
	v_mov_b32_e32 v54, v0
	v_mov_b32_e32 v55, v0
	v_mov_b32_e32 v8, v0
	v_mov_b32_e32 v9, v0
	v_mov_b32_e32 v10, v0
	v_mov_b32_e32 v11, v0
	v_mov_b32_e32 v12, v0
	v_mov_b32_e32 v13, v0
	v_mov_b32_e32 v14, v0
	v_mov_b32_e32 v15, v0
	v_mov_b32_e32 v24, v0
	v_mov_b32_e32 v25, v0
	v_mov_b32_e32 v26, v0
	v_mov_b32_e32 v27, v0
	v_mov_b32_e32 v28, v0
	v_mov_b32_e32 v29, v0
	v_mov_b32_e32 v30, v0
	v_mov_b32_e32 v31, v0
	v_mov_b32_e32 v40, v0
	v_mov_b32_e32 v41, v0
	v_mov_b32_e32 v42, v0
	v_mov_b32_e32 v43, v0
	v_mov_b32_e32 v44, v0
	v_mov_b32_e32 v45, v0
	v_mov_b32_e32 v46, v0
	v_mov_b32_e32 v47, v0
	v_mov_b32_e32 v56, v0
	v_mov_b32_e32 v57, v0
	v_mov_b32_e32 v58, v0
	v_mov_b32_e32 v59, v0
	v_mov_b32_e32 v60, v0
	v_mov_b32_e32 v61, v0
	v_mov_b32_e32 v62, v0
	v_mov_b32_e32 v63, v0
	v_mov_b32_e32 v64, v0
	v_mov_b32_e32 v65, v0
	v_mov_b32_e32 v66, v0
	v_mov_b32_e32 v67, v0
	v_mov_b32_e32 v68, v0
	v_mov_b32_e32 v69, v0
	v_mov_b32_e32 v70, v0
	v_mov_b32_e32 v71, v0
	v_mov_b32_e32 v80, v0
	v_mov_b32_e32 v81, v0
	v_mov_b32_e32 v82, v0
	v_mov_b32_e32 v83, v0
	v_mov_b32_e32 v84, v0
	v_mov_b32_e32 v85, v0
	v_mov_b32_e32 v86, v0
	v_mov_b32_e32 v87, v0
	v_mov_b32_e32 v96, v0
	v_mov_b32_e32 v97, v0
	v_mov_b32_e32 v98, v0
	v_mov_b32_e32 v99, v0
	v_mov_b32_e32 v100, v0
	v_mov_b32_e32 v101, v0
	v_mov_b32_e32 v102, v0
	v_mov_b32_e32 v103, v0
	v_mov_b32_e32 v112, v0
	v_mov_b32_e32 v113, v0
	v_mov_b32_e32 v114, v0
	v_mov_b32_e32 v115, v0
	v_mov_b32_e32 v116, v0
	v_mov_b32_e32 v117, v0
	v_mov_b32_e32 v118, v0
	v_mov_b32_e32 v119, v0
	v_mov_b32_e32 v72, v0
	v_mov_b32_e32 v73, v0
	v_mov_b32_e32 v74, v0
	v_mov_b32_e32 v75, v0
	v_mov_b32_e32 v76, v0
	v_mov_b32_e32 v77, v0
	v_mov_b32_e32 v78, v0
	v_mov_b32_e32 v79, v0
	v_mov_b32_e32 v88, v0
	v_mov_b32_e32 v89, v0
	v_mov_b32_e32 v90, v0
	v_mov_b32_e32 v91, v0
	v_mov_b32_e32 v92, v0
	v_mov_b32_e32 v93, v0
	v_mov_b32_e32 v94, v0
	v_mov_b32_e32 v95, v0
	v_mov_b32_e32 v104, v0
	v_mov_b32_e32 v105, v0
	v_mov_b32_e32 v106, v0
	v_mov_b32_e32 v107, v0
	v_mov_b32_e32 v108, v0
	v_mov_b32_e32 v109, v0
	v_mov_b32_e32 v110, v0
	v_mov_b32_e32 v111, v0
	v_mov_b32_e32 v120, v0
	v_mov_b32_e32 v121, v0
	v_mov_b32_e32 v122, v0
	v_mov_b32_e32 v123, v0
	v_mov_b32_e32 v124, v0
	v_mov_b32_e32 v125, v0
	v_mov_b32_e32 v126, v0
	v_mov_b32_e32 v127, v0
	.p2align 6

; __global__ void __launch_bounds__(NTHR, 2) fwd_kernel(Args a) {
;     ...
;             for (int it = gw2; it < IT_UP + IT_GLA + IT_FN + IT_OUT; it += NGW2) {
;                 int r = it;
;                 if (r >= IT_UP) { r -= IT_UP;
;                     if (r < IT_GLA) { transpose_item(a.in[I_WGLA], VW, DM, WglaT, (r % 64) * 32, scr, (r / 64) * 64, (r % 64) * 32, lane); continue; } r -= IT_GLA;
;                     if (r < IT_FN) { transpose_item(a.in[I_WFN], FNW, DM, WfnT, (r % 64) * 32, scr, (r / 64) * 64, (r % 64) * 32, lane); continue; } r -= IT_FN;
;                     transpose_item(a.in[I_WOUT], DM, DM, WoT, (r % 64) * 32, scr, (r / 64) * 64, (r % 64) * 32, lane); continue; }
;                 if (r < IT_UP) { const int n0 = (r % 352) * 32, j = n0 < FF ? n0 : n0 - FF; transpose_item(a.in[I_WUP], DM, F2, WupT, (j >> 7) * 256 + (n0 < FF ? 0 : 128) + (j & 127), scr, (r / 352) * 64, n0, lane); continue; } r -= IT_UP;
;                 transpose_item(a.in[I_WDN], FF, DM, WdT, (r % 64) * 32, scr, (r / 64) * 64, (r % 64) * 32, lane);
;             }
.LBB0_1030:
	s_add_i32 s55, s55, s86
	s_mov_b64 s[4:5], 0
	.p2align 6

; #define LAS __attribute__((address_space(3)))
; #define LBAR() do { asm volatile("s_waitcnt lgkmcnt(0)" ::: "memory"); __builtin_amdgcn_s_barrier(); asm volatile("" ::: "memory"); } while (0)
; __device__ __forceinline__ void gla_prep(LAS unsigned char* lds, int ufirst, int ucount, const bf16_t* Qb, const bf16_t* Kb, const bf16_t* Vb, const bf16_t* LR, ...
;     ...
;         if (fr == 0) { f32x4 dv; dv[0] = __expf(blast[0]); dv[1] = __expf(blast[1]); dv[2] = __expf(blast[2]); dv[3] = __expf(blast[3]); *(f32x4*)(DEC + kidx * 128 + 16 * wave + 4 * fq) = dv; }
;         LBAR();
; #pragma unroll
;         for (int j = 0; j < 2; ++j) { const int idx = tid + 512 * j, dd = idx >> 3, part = idx & 7;
;             *(u32x4*)(KS + (size_t)kidx * 8192 + ((((dd >> 4) * 2 + (part >> 2)) * 64 + (part & 3) * 16 + (dd & 15)) << 3)) = *(const LAS u32x4*)(ksT + dd * 72 + part * 8); }
;         if (dir == 0) {
; #pragma unroll
;             for (int j = 0; j < 4; ++j) { const int idx = tid + 512 * j, v = idx >> 3, part = idx & 7;
;                 *(u32x4*)(VT + (size_t)(bh * GLA_NCH + cidx) * 16384 + ((((v >> 4) * 2 + (part >> 2)) * 64 + (part & 3) * 16 + (v & 15)) << 3)) = *(const LAS u32x4*)(vT + v * 72 + part * 8); }
.LBB0_1191:
	s_lshl_b32 s14, s12, 1
	s_add_i32 s13, s14, s13
	s_mul_i32 s14, s13, 36
	s_add_i32 s46, s14, s11
	s_and_saveexec_b64 s[48:49], s[6:7]
	s_cbranch_execz .LBB0_1193
	v_mul_f32_e32 v0, 0x3fb8aa3b, v0
	v_mul_f32_e32 v1, 0x3fb8aa3b, v1
	v_mul_f32_e32 v2, 0x3fb8aa3b, v2
	v_mul_f32_e32 v3, 0x3fb8aa3b, v3
	v_exp_f32_e32 v0, v0
	v_exp_f32_e32 v1, v1
	v_exp_f32_e32 v2, v2
	v_exp_f32_e32 v3, v3
	s_lshl_b32 s68, s46, 7
	s_ashr_i32 s69, s68, 31
	v_lshl_add_u64 v[4:5], s[68:69], 2, v[32:33]
	global_store_dwordx4 v[4:5], v[0:3], off sc1
.LBB0_1193:
	s_or_b64 exec, exec, s[48:49]
	s_waitcnt lgkmcnt(0)
	s_barrier
	v_add_u32_e32 v0, v76, v85
	s_ashr_i32 s47, s46, 31
	ds_read_b128 v[0:3], v0
	s_lshl_b64 s[46:47], s[46:47], 14
	s_add_u32 s46, s64, s46
	s_addc_u32 s47, s65, s47
	v_lshl_add_u64 v[4:5], v[42:43], 1, s[46:47]
	s_waitcnt lgkmcnt(0)
	global_store_dwordx4 v[4:5], v[0:3], off sc1
	v_lshl_add_u64 v[4:5], v[44:45], 1, s[46:47]
	s_andn2_b64 vcc, exec, s[42:43]
	v_add_u32_e32 v0, v76, v86
	ds_read_b128 v[0:3], v0
	s_waitcnt lgkmcnt(0)
	global_store_dwordx4 v[4:5], v[0:3], off sc1
	s_cbranch_vccnz .LBB0_1195
	s_mul_i32 s12, s12, 36
	s_add_i32 s46, s12, s11
	v_add_u32_e32 v0, v77, v85
	s_ashr_i32 s47, s46, 31
	ds_read_b128 v[0:3], v0 offset:44032
	s_lshl_b64 s[46:47], s[46:47], 15
	s_add_u32 s46, s54, s46
	s_addc_u32 s47, s55, s47
	v_lshl_add_u64 v[4:5], v[42:43], 1, s[46:47]
	s_waitcnt lgkmcnt(0)
	global_store_dwordx4 v[4:5], v[0:3], off sc1
	v_lshl_add_u64 v[4:5], v[44:45], 1, s[46:47]
	s_nop 0
	v_add_u32_e32 v0, v77, v86
	ds_read_b128 v[0:3], v0 offset:44032
	s_waitcnt lgkmcnt(0)
	global_store_dwordx4 v[4:5], v[0:3], off sc1
	ds_read_b128 v[0:3], v96 offset:44032
	v_lshl_add_u64 v[4:5], v[46:47], 1, s[46:47]
	s_waitcnt lgkmcnt(0)
	global_store_dwordx4 v[4:5], v[0:3], off sc1
	ds_read_b128 v[0:3], v97 offset:44032
	v_lshl_add_u64 v[4:5], v[48:49], 1, s[46:47]
	s_waitcnt lgkmcnt(0)
	global_store_dwordx4 v[4:5], v[0:3], off sc1
	s_and_b64 vcc, exec, s[44:45]
	s_cbranch_vccnz .LBB0_1100
	s_branch .LBB0_1196

; #define LAS __attribute__((address_space(3)))
; __device__ __forceinline__ f32x4 mma16(bf16x8 afrag, bf16x8 bfrag, f32x4 acc) { return __builtin_amdgcn_mfma_f32_16x16x32_bf16(bfrag, afrag, acc, 0, 0, 0); }
; #define LBAR() do { asm volatile("s_waitcnt lgkmcnt(0)" ::: "memory"); __builtin_amdgcn_s_barrier(); asm volatile("" ::: "memory"); } while (0)
; __device__ __forceinline__ void gla_prep(LAS unsigned char* lds, int ufirst, int ucount, const bf16_t* Qb, const bf16_t* Kb, const bf16_t* Vb, const bf16_t* LR, ...
;     ...
;         if (lat) {
; #pragma unroll
;             for (int j = 0; j < 2; ++j) { const int idx = tid + 512 * j, pr = idx >> 4, part = idx & 15;
;                 *(u32x4*)(QD + (size_t)qidx * 8192 + ((((pr >> 4) * 4 + (part >> 2)) * 64 + (part & 3) * 16 + (pr & 15)) << 3)) = *(const LAS u32x4*)(qd + pr * 136 + part * 8); }
;             { const int ct = wave >> 1; f32x4 acc[2] = {(f32x4){0.f, 0.f, 0.f, 0.f}, (f32x4){0.f, 0.f, 0.f, 0.f}};
; #pragma unroll
;                 for (int k0 = 0; k0 < 4; ++k0) { const bf16x8 af = *(const LAS bf16x8*)(qd + (16 * ct + fr) * 136 + k0 * 32 + fq * 8);
; #pragma unroll
;                     for (int j = 0; j < 2; ++j) { const int st = (wave & 1) * 2 + j; const bf16x8 bf = *(const LAS bf16x8*)(kd + (16 * st + fr) * 136 + k0 * 32 + fq * 8); acc[j] = mma16(af, bf, acc[j]); } }
; #pragma unroll
;                 for (int j = 0; j < 2; ++j) { const int st = (wave & 1) * 2 + j, c = 16 * ct + fr; f32x4 v = acc[j];
; #pragma unroll
;                     for (int i = 0; i < 4; ++i) { const int sp = 16 * st + 4 * fq + i; const bool keep = dir ? (sp >= c) : (sp <= c); v[i] = keep ? v[i] : 0.f; }
;                     u32x2 w; w.x = pk2hw(v[0], v[1]); w.y = pk2hw(v[2], v[3]); *(LAS u32x2*)(sc + c * 72 + 16 * st + 4 * fq) = w; }
;             }
;             LBAR();
.LBB0_1196:
	ds_read_b128 v[0:3], v100 offset:17408
	ds_read_b128 v[4:7], v78
	ds_read_b128 v[8:11], v100 offset:21760
	ds_read_b128 v[12:15], v100 offset:17472
	ds_read_b128 v[20:23], v100 offset:21824
	ds_read_b128 v[16:19], v78 offset:64
	s_waitcnt lgkmcnt(4)
	v_mfma_f32_16x16x32_bf16 v[0:3], v[0:3], v[4:7], 0
	s_lshl_b32 s12, s13, 5
	s_add_i32 s11, s11, -4
	s_add_i32 s12, s11, s12
	s_waitcnt lgkmcnt(3)
	v_mfma_f32_16x16x32_bf16 v[4:7], v[8:11], v[4:7], 0
	ds_read_b128 v[8:11], v100 offset:17536
	s_ashr_i32 s13, s12, 31
	s_lshl_b64 s[12:13], s[12:13], 14
	s_waitcnt lgkmcnt(1)
	v_mfma_f32_16x16x32_bf16 v[0:3], v[12:15], v[16:19], v[0:3]
	ds_read_b128 v[12:15], v78 offset:128
	ds_read_b128 v[56:59], v100 offset:21888
	s_add_u32 s12, s86, s12
	s_addc_u32 s13, s87, s13
	v_mfma_f32_16x16x32_bf16 v[4:7], v[20:23], v[16:19], v[4:7]
	ds_read_b128 v[16:19], v78 offset:192
	ds_read_b128 v[20:23], v100 offset:17600
	v_mov_b32_e32 v55, v27
	s_waitcnt lgkmcnt(3)
	v_mfma_f32_16x16x32_bf16 v[0:3], v[8:11], v[12:15], v[0:3]
	ds_read_b128 v[8:11], v98
	ds_read_b128 v[60:63], v100 offset:21952
	s_waitcnt lgkmcnt(4)
	v_mfma_f32_16x16x32_bf16 v[4:7], v[56:59], v[12:15], v[4:7]
	ds_read_b128 v[12:15], v99
	v_lshl_add_u64 v[56:57], v[50:51], 1, s[12:13]
	s_waitcnt lgkmcnt(2)
	global_store_dwordx4 v[56:57], v[8:11], off sc1
	v_mfma_f32_16x16x32_bf16 v[0:3], v[20:23], v[16:19], v[0:3]
	s_nop 0
	v_lshl_add_u64 v[8:9], v[52:53], 1, s[12:13]
	v_readlane_b32 s12, v255, 1
	v_readlane_b32 s13, v255, 2
	s_waitcnt lgkmcnt(0)
	global_store_dwordx4 v[8:9], v[12:15], off sc1
	s_nop 1
	v_cvt_pk_bf16_f32 v0, v0, s0
	v_cndmask_b32_e64 v8, 0, 1, s[12:13]
	v_readlane_b32 s12, v254, 63
	v_readlane_b32 s13, v255, 0
	v_cvt_pk_bf16_f32 v1, v1, s0
	v_mfma_f32_16x16x32_bf16 v[4:7], v[60:63], v[16:19], v[4:7]
	v_cndmask_b32_e64 v9, 0, 1, s[12:13]
	v_readlane_b32 s12, v255, 5
	v_readlane_b32 s13, v255, 6
	v_cndmask_b32_e64 v8, v9, v8, s[42:43]
	v_and_b32_e32 v8, 1, v8
	v_cndmask_b32_e64 v9, 0, 1, s[12:13]
	v_readlane_b32 s12, v255, 3
	v_readlane_b32 s13, v255, 4
	v_cmp_eq_u32_e32 vcc, 1, v8
	v_cvt_pk_bf16_f32 v4, v4, s0
	v_cndmask_b32_e64 v10, 0, 1, s[12:13]
	v_readlane_b32 s12, v255, 9
	v_readlane_b32 s13, v255, 10
	v_cndmask_b32_e64 v9, v10, v9, s[42:43]
	v_and_b32_e32 v9, 1, v9
	v_cndmask_b32_e64 v10, 0, 1, s[12:13]
	v_readlane_b32 s12, v255, 7
	v_readlane_b32 s13, v255, 8
	v_cndmask_b32_e32 v0, 0, v0, vcc
	v_cmp_eq_u32_e32 vcc, 1, v9
	v_cndmask_b32_e64 v11, 0, 1, s[12:13]
	v_readlane_b32 s12, v255, 13
	v_readlane_b32 s13, v255, 14
	v_cndmask_b32_e64 v10, v11, v10, s[42:43]
	v_and_b32_e32 v10, 1, v10
	v_cndmask_b32_e64 v11, 0, 1, s[12:13]
	v_readlane_b32 s12, v255, 11
	v_readlane_b32 s13, v255, 12
	v_cndmask_b32_e32 v1, 0, v1, vcc
	v_perm_b32 v0, v1, v0, s71
	v_cndmask_b32_e64 v12, 0, 1, s[12:13]
	v_cndmask_b32_e64 v11, v12, v11, s[42:43]
	v_and_b32_e32 v11, 1, v11
	v_cvt_pk_bf16_f32 v1, v2, s0
	v_cmp_eq_u32_e32 vcc, 1, v10
	v_cvt_pk_bf16_f32 v2, v3, s0
	v_readlane_b32 s12, v255, 17
	v_cndmask_b32_e32 v1, 0, v1, vcc
	v_cmp_eq_u32_e32 vcc, 1, v11
	v_readlane_b32 s13, v255, 18
	v_cndmask_b32_e64 v3, 0, 1, s[34:35]
	v_cndmask_b32_e32 v2, 0, v2, vcc
	v_perm_b32 v1, v2, v1, s71
	v_add_u32_e32 v2, s75, v79
	ds_write_b64 v2, v[0:1] offset:34816
	v_cndmask_b32_e64 v0, 0, 1, s[12:13]
	v_readlane_b32 s12, v255, 15
	v_readlane_b32 s13, v255, 16
	v_cndmask_b32_e64 v8, 0, 1, s[38:39]
	s_nop 0
	v_cndmask_b32_e64 v1, 0, 1, s[12:13]
	v_readlane_b32 s12, v255, 21
	v_readlane_b32 s13, v255, 22
	v_cndmask_b32_e64 v0, v1, v0, s[42:43]
	v_and_b32_e32 v0, 1, v0
	v_cndmask_b32_e64 v1, 0, 1, s[12:13]
	v_readlane_b32 s12, v255, 19
	v_readlane_b32 s13, v255, 20
	v_cmp_eq_u32_e32 vcc, 1, v0
	s_nop 0
	v_cndmask_b32_e64 v2, 0, 1, s[12:13]
	v_cndmask_b32_e64 v1, v2, v1, s[42:43]
	v_and_b32_e32 v1, 1, v1
	v_cndmask_b32_e64 v2, 0, 1, s[36:37]
	v_cndmask_b32_e64 v2, v3, v2, s[42:43]
	v_cndmask_b32_e64 v3, 0, 1, s[40:41]
	v_cndmask_b32_e32 v0, 0, v4, vcc
	v_cvt_pk_bf16_f32 v4, v5, s0
	v_cmp_eq_u32_e32 vcc, 1, v1
	v_and_b32_e32 v2, 1, v2
	v_cndmask_b32_e64 v3, v8, v3, s[42:43]
	v_cndmask_b32_e32 v1, 0, v4, vcc
	v_and_b32_e32 v3, 1, v3
	v_perm_b32 v0, v1, v0, s71
	v_cvt_pk_bf16_f32 v1, v6, s0
	v_cmp_eq_u32_e32 vcc, 1, v2
	v_cvt_pk_bf16_f32 v2, v7, s0
	s_and_b64 s[12:13], s[42:43], exec
	v_cndmask_b32_e32 v1, 0, v1, vcc
	v_cmp_eq_u32_e32 vcc, 1, v3
	s_cselect_b32 s13, s83, s81
	s_cselect_b32 s12, s82, s80
	v_cndmask_b32_e32 v2, 0, v2, vcc
	v_perm_b32 v1, v2, v1, s71
	v_add_u32_e32 v2, s76, v79
	ds_write_b64 v2, v[0:1] offset:34816
	s_waitcnt lgkmcnt(0)
	s_barrier
; #define LAS __attribute__((address_space(3)))
; __device__ __forceinline__ void st_bf4(bf16_t* p, f32x4 v) { u32x2 w; w.x = pk2(v[0], v[1]); w.y = pk2(v[2], v[3]); *(u32x2*)p = w; }
; __device__ __forceinline__ f32x4 mma16(bf16x8 afrag, bf16x8 bfrag, f32x4 acc) { return __builtin_amdgcn_mfma_f32_16x16x32_bf16(bfrag, afrag, acc, 0, 0, 0); }
; __device__ __forceinline__ void gla_prep(LAS unsigned char* lds, int ufirst, int ucount, const bf16_t* Qb, const bf16_t* Kb, const bf16_t* Vb, const bf16_t* LR, ...
;     ...
;             { f32x4 acc[4][2];
; #pragma unroll
;                 for (int ct = 0; ct < 4; ++ct) { acc[ct][0] = (f32x4){0.f, 0.f, 0.f, 0.f}; acc[ct][1] = (f32x4){0.f, 0.f, 0.f, 0.f}; }
; #pragma unroll
;                 for (int k0 = 0; k0 < 2; ++k0) { bf16x8 bf[2];
; #pragma unroll
;                     for (int j = 0; j < 2; ++j) bf[j] = *(const LAS bf16x8*)(vT + (16 * (2 * wave + j) + fr) * 72 + k0 * 32 + fq * 8);
; #pragma unroll
;                     for (int ct = 0; ct < 4; ++ct) { const bf16x8 af = *(const LAS bf16x8*)(sc + (16 * ct + fr) * 72 + k0 * 32 + fq * 8);
;                         acc[ct][0] = mma16(af, bf[0], acc[ct][0]); acc[ct][1] = mma16(af, bf[1], acc[ct][1]); } }
;                 bf16_t* O = dir ? Ob : Of;
; #pragma unroll
;                 for (int ct = 0; ct < 4; ++ct)
; #pragma unroll
;                     for (int j = 0; j < 2; ++j) st_bf4(O + (((((((size_t)(b * 32 + cidx - 4) * 4 + h) * 8 + wave) * 4 + ct) * 2 + j) * 64 + lane) << 2), acc[ct][j]);
	ds_read_b128 v[0:3], v101 offset:44032
	ds_read_b128 v[4:7], v102 offset:34816
	ds_read_b128 v[12:15], v101 offset:46336
	ds_read_b128 v[68:71], v101 offset:44096
	ds_read_b128 v[16:19], v102 offset:37120
	ds_read_b128 v[56:59], v102 offset:39424
	ds_read_b128 v[64:67], v102 offset:41728
	s_waitcnt lgkmcnt(5)
	v_mfma_f32_16x16x32_bf16 v[8:11], v[0:3], v[4:7], 0
	ds_read_b128 v[72:75], v101 offset:46400
	s_lshl_b32 s9, s9, 5
	s_add_i32 s42, s11, s9
	s_waitcnt lgkmcnt(5)
	v_mfma_f32_16x16x32_bf16 v[4:7], v[12:15], v[4:7], 0
	s_ashr_i32 s43, s42, 31
	s_lshl_b32 s9, s10, 3
	s_add_u32 s10, s9, s73
	s_waitcnt lgkmcnt(3)
	v_mfma_f32_16x16x32_bf16 v[20:23], v[0:3], v[16:19], 0
	v_readlane_b32 s9, v254, 62
	s_addc_u32 s11, 0, s9
	s_lshl_b64 s[10:11], s[10:11], 12
	v_mfma_f32_16x16x32_bf16 v[16:19], v[12:15], v[16:19], 0
	s_waitcnt lgkmcnt(2)
	v_mfma_f32_16x16x32_bf16 v[60:63], v[0:3], v[56:59], 0
	v_mfma_f32_16x16x32_bf16 v[56:59], v[12:15], v[56:59], 0
	s_waitcnt lgkmcnt(1)
	v_mfma_f32_16x16x32_bf16 v[0:3], v[0:3], v[64:67], 0
	v_mfma_f32_16x16x32_bf16 v[12:15], v[12:15], v[64:67], 0
	ds_read_b128 v[64:67], v102 offset:34880
	s_waitcnt lgkmcnt(0)
	v_mfma_f32_16x16x32_bf16 v[8:11], v[68:71], v[64:67], v[8:11]
	v_mfma_f32_16x16x32_bf16 v[4:7], v[72:75], v[64:67], v[4:7]
	ds_read_b128 v[64:67], v102 offset:37184
	s_nop 5
	v_cvt_pk_bf16_f32 v8, v8, v9
	v_cvt_pk_bf16_f32 v9, v10, v11
	s_waitcnt lgkmcnt(0)
	v_mfma_f32_16x16x32_bf16 v[20:23], v[68:71], v[64:67], v[20:23]
	v_cvt_pk_bf16_f32 v4, v4, v5
	v_mfma_f32_16x16x32_bf16 v[16:19], v[72:75], v[64:67], v[16:19]
	ds_read_b128 v[64:67], v102 offset:39488
	v_cvt_pk_bf16_f32 v5, v6, v7
	s_waitcnt lgkmcnt(0)
	v_mfma_f32_16x16x32_bf16 v[60:63], v[68:71], v[64:67], v[60:63]
	v_mfma_f32_16x16x32_bf16 v[56:59], v[72:75], v[64:67], v[56:59]
	ds_read_b128 v[64:67], v102 offset:41792
	s_waitcnt lgkmcnt(0)
	v_mfma_f32_16x16x32_bf16 v[0:3], v[68:71], v[64:67], v[0:3]
	v_mfma_f32_16x16x32_bf16 v[12:15], v[72:75], v[64:67], v[12:15]
	v_lshl_add_u64 v[64:65], s[12:13], 0, v[54:55]
	s_lshl_b64 s[12:13], s[42:43], 17
	v_lshl_add_u64 v[64:65], v[64:65], 0, s[12:13]
	v_lshl_add_u64 v[64:65], v[64:65], 0, s[10:11]
	global_store_dwordx2 v[64:65], v[4:5], off offset:512 sc1
	v_cvt_pk_bf16_f32 v4, v20, v21
	v_cvt_pk_bf16_f32 v5, v22, v23
	global_store_dwordx2 v[64:65], v[4:5], off offset:1024 sc1
	v_cvt_pk_bf16_f32 v4, v16, v17
	v_cvt_pk_bf16_f32 v5, v18, v19
	global_store_dwordx2 v[64:65], v[4:5], off offset:1536 sc1
	v_cvt_pk_bf16_f32 v4, v60, v61
	v_cvt_pk_bf16_f32 v5, v62, v63
	v_cvt_pk_bf16_f32 v0, v0, v1
	v_cvt_pk_bf16_f32 v1, v2, v3
	global_store_dwordx2 v[64:65], v[4:5], off offset:2048 sc1
	v_cvt_pk_bf16_f32 v4, v56, v57
	v_cvt_pk_bf16_f32 v5, v58, v59
	global_store_dwordx2 v[64:65], v[0:1], off offset:3072 sc1
	v_cvt_pk_bf16_f32 v0, v12, v13
	v_cvt_pk_bf16_f32 v1, v14, v15
	global_store_dwordx2 v[64:65], v[8:9], off sc1
	global_store_dwordx2 v[64:65], v[4:5], off offset:2560 sc1
	global_store_dwordx2 v[64:65], v[0:1], off offset:3584 sc1
	s_branch .LBB0_1100

;     __device__ __forceinline__ bool next(int i, Unit& u) const { return decode(i * G + c, u); }
; template <class Epi, class Sched, bool DEFER>
; __device__ __forceinline__ void gemm_fast_core(LAS unsigned char* lds, const GemmP g, const Sched& S, const Epi& E, f32x4 (&acc)[2][2][4][2], Unit& cur) {
;     ...
;     for (;;) {
;         const bool has_next = S.next(ui + 1, nxt);
;         const char* nA = has_next ? (const char*)g.aptr(nxt) : cA; const char* nB = has_next ? (const char*)g.bptr(nxt) : cB;
;         for (int t = 0; t < nt; t += 2) {
;             const bool last = (t == nt - 2);
;             const char* a1 = cA + (size_t)(t + 1) * kstep;
;             const char* a2 = last ? nA : cA + (size_t)(t + 2) * kstep; const char* b2 = last ? nB : cB + (size_t)(t + 2) * kstep;
;     ...
;         for (int a = 0; a < 2; ++a)
; #pragma unroll
;             for (int b = 0; b < 2; ++b)
; #pragma unroll
;                 for (int m = 0; m < 4; ++m)
; #pragma unroll
;                     for (int n = 0; n < 2; ++n) acc[a][b][m][n] = (f32x4){0.f, 0.f, 0.f, 0.f};
.LBB0_1218:
	s_ashr_i32 s17, s16, 31
	s_lshl_b64 s[20:21], s[16:17], 21
	s_add_u32 s20, s48, s20
	s_addc_u32 s21, s49, s21
	s_and_b64 s[26:27], s[26:27], exec
	s_cselect_b32 s17, s21, s23
	s_cselect_b32 s41, s20, s22
	s_add_u32 s22, s22, 0x100080
	s_addc_u32 s23, s23, 0
	s_add_u32 s42, s24, 0x100
	v_mov_b32_e32 v0, 0
	s_addc_u32 s43, s25, 0
	s_mov_b32 s44, -2
	v_mov_b32_e32 v1, v0
	v_mov_b32_e32 v2, v0
	v_mov_b32_e32 v3, v0
	v_mov_b32_e32 v4, v0
	v_mov_b32_e32 v5, v0
	v_mov_b32_e32 v6, v0
	v_mov_b32_e32 v7, v0
	v_mov_b32_e32 v12, v0
	v_mov_b32_e32 v13, v0
	v_mov_b32_e32 v14, v0
	v_mov_b32_e32 v15, v0
	v_mov_b32_e32 v20, v0
	v_mov_b32_e32 v21, v0
	v_mov_b32_e32 v22, v0
	v_mov_b32_e32 v23, v0
	v_mov_b32_e32 v28, v0
	v_mov_b32_e32 v29, v0
	v_mov_b32_e32 v30, v0
	v_mov_b32_e32 v31, v0
	v_mov_b32_e32 v36, v0
	v_mov_b32_e32 v37, v0
	v_mov_b32_e32 v38, v0
	v_mov_b32_e32 v39, v0
	v_mov_b32_e32 v44, v0
	v_mov_b32_e32 v45, v0
	v_mov_b32_e32 v46, v0
	v_mov_b32_e32 v47, v0
	v_mov_b32_e32 v52, v0
	v_mov_b32_e32 v53, v0
	v_mov_b32_e32 v54, v0
	v_mov_b32_e32 v55, v0
	v_mov_b32_e32 v8, v0
	v_mov_b32_e32 v9, v0
	v_mov_b32_e32 v10, v0
	v_mov_b32_e32 v11, v0
	v_mov_b32_e32 v16, v0
	v_mov_b32_e32 v17, v0
	v_mov_b32_e32 v18, v0
	v_mov_b32_e32 v19, v0
	v_mov_b32_e32 v24, v0
	v_mov_b32_e32 v25, v0
	v_mov_b32_e32 v26, v0
	v_mov_b32_e32 v27, v0
	v_mov_b32_e32 v32, v0
	v_mov_b32_e32 v33, v0
	v_mov_b32_e32 v34, v0
	v_mov_b32_e32 v35, v0
	v_mov_b32_e32 v40, v0
	v_mov_b32_e32 v41, v0
	v_mov_b32_e32 v42, v0
	v_mov_b32_e32 v43, v0
	v_mov_b32_e32 v48, v0
	v_mov_b32_e32 v49, v0
	v_mov_b32_e32 v50, v0
	v_mov_b32_e32 v51, v0
	v_mov_b32_e32 v56, v0
	v_mov_b32_e32 v57, v0
	v_mov_b32_e32 v58, v0
	v_mov_b32_e32 v59, v0
	v_mov_b32_e32 v60, v0
	v_mov_b32_e32 v61, v0
	v_mov_b32_e32 v62, v0
	v_mov_b32_e32 v63, v0
	v_mov_b32_e32 v64, v0
	v_mov_b32_e32 v65, v0
	v_mov_b32_e32 v66, v0
	v_mov_b32_e32 v67, v0
	v_mov_b32_e32 v68, v0
	v_mov_b32_e32 v69, v0
	v_mov_b32_e32 v70, v0
	v_mov_b32_e32 v71, v0
	v_mov_b32_e32 v76, v0
	v_mov_b32_e32 v77, v0
	v_mov_b32_e32 v78, v0
	v_mov_b32_e32 v79, v0
	v_mov_b32_e32 v84, v0
	v_mov_b32_e32 v85, v0
	v_mov_b32_e32 v86, v0
	v_mov_b32_e32 v87, v0
	v_mov_b32_e32 v92, v0
	v_mov_b32_e32 v93, v0
	v_mov_b32_e32 v94, v0
	v_mov_b32_e32 v95, v0
	v_mov_b32_e32 v100, v0
	v_mov_b32_e32 v101, v0
	v_mov_b32_e32 v102, v0
	v_mov_b32_e32 v103, v0
	v_mov_b32_e32 v108, v0
	v_mov_b32_e32 v109, v0
	v_mov_b32_e32 v110, v0
	v_mov_b32_e32 v111, v0
	v_mov_b32_e32 v116, v0
	v_mov_b32_e32 v117, v0
	v_mov_b32_e32 v118, v0
	v_mov_b32_e32 v119, v0
	v_mov_b32_e32 v72, v0
	v_mov_b32_e32 v73, v0
	v_mov_b32_e32 v74, v0
	v_mov_b32_e32 v75, v0
	v_mov_b32_e32 v80, v0
	v_mov_b32_e32 v81, v0
	v_mov_b32_e32 v82, v0
	v_mov_b32_e32 v83, v0
	v_mov_b32_e32 v88, v0
	v_mov_b32_e32 v89, v0
	v_mov_b32_e32 v90, v0
	v_mov_b32_e32 v91, v0
	v_mov_b32_e32 v96, v0
	v_mov_b32_e32 v97, v0
	v_mov_b32_e32 v98, v0
	v_mov_b32_e32 v99, v0
	v_mov_b32_e32 v104, v0
	v_mov_b32_e32 v105, v0
	v_mov_b32_e32 v106, v0
	v_mov_b32_e32 v107, v0
	v_mov_b32_e32 v112, v0
	v_mov_b32_e32 v113, v0
	v_mov_b32_e32 v114, v0
	v_mov_b32_e32 v115, v0
	v_mov_b32_e32 v120, v0
	v_mov_b32_e32 v121, v0
	v_mov_b32_e32 v122, v0
	v_mov_b32_e32 v123, v0
	v_mov_b32_e32 v124, v0
	v_mov_b32_e32 v125, v0
	v_mov_b32_e32 v126, v0
	v_mov_b32_e32 v127, v0
	.p2align 6

;     __device__ __forceinline__ bool next(int i, Unit& u) const { return decode(i * G + c, u); }
; template <class Epi, class Sched, bool DEFER>
; __device__ __forceinline__ void gemm_fast_core(LAS unsigned char* lds, const GemmP g, const Sched& S, const Epi& E, f32x4 (&acc)[2][2][4][2], Unit& cur) {
;     ...
;     for (;;) {
;         const bool has_next = S.next(ui + 1, nxt);
;         const char* nA = has_next ? (const char*)g.aptr(nxt) : cA; const char* nB = has_next ? (const char*)g.bptr(nxt) : cB;
;         for (int t = 0; t < nt; t += 2) {
;             const bool last = (t == nt - 2);
;             const char* a1 = cA + (size_t)(t + 1) * kstep;
;             const char* a2 = last ? nA : cA + (size_t)(t + 2) * kstep; const char* b2 = last ? nB : cB + (size_t)(t + 2) * kstep;
;     ...
;         for (int a = 0; a < 2; ++a)
; #pragma unroll
;             for (int b = 0; b < 2; ++b)
; #pragma unroll
;                 for (int m = 0; m < 4; ++m)
; #pragma unroll
;                     for (int n = 0; n < 2; ++n) acc[a][b][m][n] = (f32x4){0.f, 0.f, 0.f, 0.f};
.LBB0_1409:
	s_xor_b64 s[28:29], s[20:21], -1
	s_ashr_i32 s13, s12, 31
	s_and_b64 vcc, exec, s[28:29]
	s_lshl_b64 s[22:23], s[12:13], 19
	s_add_u32 s22, s78, s22
	s_addc_u32 s23, s79, s23
	s_and_b64 s[24:25], s[20:21], exec
	s_cselect_b32 s5, s23, s31
	s_cselect_b32 s13, s22, s30
	s_ashr_i32 s11, s10, 31
	s_lshl_b64 s[24:25], s[10:11], 19
	s_add_u32 s24, s74, s24
	s_addc_u32 s25, s75, s25
	s_and_b64 s[36:37], s[20:21], exec
	s_cselect_b32 s11, s25, s35
	s_cselect_b32 s27, s24, s34
	s_add_u32 s30, s30, 0x40080
	s_addc_u32 s31, s31, 0
	s_add_u32 s33, s34, 0x100
	v_mov_b32_e32 v0, 0
	s_addc_u32 s47, s35, 0
	s_mov_b32 s48, -2
	v_mov_b32_e32 v1, v0
	v_mov_b32_e32 v2, v0
	v_mov_b32_e32 v3, v0
	v_mov_b32_e32 v4, v0
	v_mov_b32_e32 v5, v0
	v_mov_b32_e32 v6, v0
	v_mov_b32_e32 v7, v0
	v_mov_b32_e32 v16, v0
	v_mov_b32_e32 v17, v0
	v_mov_b32_e32 v18, v0
	v_mov_b32_e32 v19, v0
	v_mov_b32_e32 v20, v0
	v_mov_b32_e32 v21, v0
	v_mov_b32_e32 v22, v0
	v_mov_b32_e32 v23, v0
	v_mov_b32_e32 v32, v0
	v_mov_b32_e32 v33, v0
	v_mov_b32_e32 v34, v0
	v_mov_b32_e32 v35, v0
	v_mov_b32_e32 v36, v0
	v_mov_b32_e32 v37, v0
	v_mov_b32_e32 v38, v0
	v_mov_b32_e32 v39, v0
	v_mov_b32_e32 v48, v0
	v_mov_b32_e32 v49, v0
	v_mov_b32_e32 v50, v0
	v_mov_b32_e32 v51, v0
	v_mov_b32_e32 v52, v0
	v_mov_b32_e32 v53, v0
	v_mov_b32_e32 v54, v0
	v_mov_b32_e32 v55, v0
	v_mov_b32_e32 v8, v0
	v_mov_b32_e32 v9, v0
	v_mov_b32_e32 v10, v0
	v_mov_b32_e32 v11, v0
	v_mov_b32_e32 v12, v0
	v_mov_b32_e32 v13, v0
	v_mov_b32_e32 v14, v0
	v_mov_b32_e32 v15, v0
	v_mov_b32_e32 v24, v0
	v_mov_b32_e32 v25, v0
	v_mov_b32_e32 v26, v0
	v_mov_b32_e32 v27, v0
	v_mov_b32_e32 v28, v0
	v_mov_b32_e32 v29, v0
	v_mov_b32_e32 v30, v0
	v_mov_b32_e32 v31, v0
	v_mov_b32_e32 v40, v0
	v_mov_b32_e32 v41, v0
	v_mov_b32_e32 v42, v0
	v_mov_b32_e32 v43, v0
	v_mov_b32_e32 v44, v0
	v_mov_b32_e32 v45, v0
	v_mov_b32_e32 v46, v0
	v_mov_b32_e32 v47, v0
	s_waitcnt vmcnt(0)
	v_mov_b32_e32 v56, v0
	v_mov_b32_e32 v57, v0
	v_mov_b32_e32 v58, v0
	v_mov_b32_e32 v59, v0
	v_mov_b32_e32 v60, v0
	v_mov_b32_e32 v61, v0
	v_mov_b32_e32 v62, v0
	v_mov_b32_e32 v63, v0
	v_mov_b32_e32 v64, v0
	v_mov_b32_e32 v65, v0
	v_mov_b32_e32 v66, v0
	v_mov_b32_e32 v67, v0
	v_mov_b32_e32 v68, v0
	v_mov_b32_e32 v69, v0
	v_mov_b32_e32 v70, v0
	v_mov_b32_e32 v71, v0
	v_mov_b32_e32 v80, v0
	v_mov_b32_e32 v81, v0
	v_mov_b32_e32 v82, v0
	v_mov_b32_e32 v83, v0
	v_mov_b32_e32 v84, v0
	v_mov_b32_e32 v85, v0
	v_mov_b32_e32 v86, v0
	v_mov_b32_e32 v87, v0
	v_mov_b32_e32 v96, v0
	v_mov_b32_e32 v97, v0
	v_mov_b32_e32 v98, v0
	v_mov_b32_e32 v99, v0
	v_mov_b32_e32 v100, v0
	v_mov_b32_e32 v101, v0
	v_mov_b32_e32 v102, v0
	v_mov_b32_e32 v103, v0
	v_mov_b32_e32 v112, v0
	v_mov_b32_e32 v113, v0
	v_mov_b32_e32 v114, v0
	v_mov_b32_e32 v115, v0
	v_mov_b32_e32 v116, v0
	v_mov_b32_e32 v117, v0
	v_mov_b32_e32 v118, v0
	v_mov_b32_e32 v119, v0
	v_mov_b32_e32 v72, v0
	v_mov_b32_e32 v73, v0
	v_mov_b32_e32 v74, v0
	v_mov_b32_e32 v75, v0
	v_mov_b32_e32 v76, v0
	v_mov_b32_e32 v77, v0
	v_mov_b32_e32 v78, v0
	v_mov_b32_e32 v79, v0
	v_mov_b32_e32 v88, v0
	v_mov_b32_e32 v89, v0
	v_mov_b32_e32 v90, v0
	v_mov_b32_e32 v91, v0
	v_mov_b32_e32 v92, v0
	v_mov_b32_e32 v93, v0
	v_mov_b32_e32 v94, v0
	v_mov_b32_e32 v95, v0
	v_mov_b32_e32 v104, v0
	v_mov_b32_e32 v105, v0
	v_mov_b32_e32 v106, v0
	v_mov_b32_e32 v107, v0
	v_mov_b32_e32 v108, v0
	v_mov_b32_e32 v109, v0
	v_mov_b32_e32 v110, v0
	v_mov_b32_e32 v111, v0
	v_mov_b32_e32 v120, v0
	v_mov_b32_e32 v121, v0
	v_mov_b32_e32 v122, v0
	v_mov_b32_e32 v123, v0
	v_mov_b32_e32 v124, v0
	v_mov_b32_e32 v125, v0
	v_mov_b32_e32 v126, v0
	v_mov_b32_e32 v127, v0
	.p2align 6

;     __device__ __forceinline__ bool next(int i, Unit& u) const { return decode(i * G + c, u); }
; template <class Epi, class Sched, bool DEFER>
; __device__ __forceinline__ void gemm_fast_core(LAS unsigned char* lds, const GemmP g, const Sched& S, const Epi& E, f32x4 (&acc)[2][2][4][2], Unit& cur) {
;     ...
;     for (;;) {
;         const bool has_next = S.next(ui + 1, nxt);
;         const char* nA = has_next ? (const char*)g.aptr(nxt) : cA; const char* nB = has_next ? (const char*)g.bptr(nxt) : cB;
;         for (int t = 0; t < nt; t += 2) {
;             const bool last = (t == nt - 2);
;             const char* a1 = cA + (size_t)(t + 1) * kstep;
;             const char* a2 = last ? nA : cA + (size_t)(t + 2) * kstep; const char* b2 = last ? nB : cB + (size_t)(t + 2) * kstep;
;     ...
;         for (int a = 0; a < 2; ++a)
; #pragma unroll
;             for (int b = 0; b < 2; ++b)
; #pragma unroll
;                 for (int m = 0; m < 4; ++m)
; #pragma unroll
;                     for (int n = 0; n < 2; ++n) acc[a][b][m][n] = (f32x4){0.f, 0.f, 0.f, 0.f};
.LBB0_1614:
	s_ashr_i32 s1, s0, 31
	s_lshl_b64 s[14:15], s[0:1], 20
	s_add_u32 s14, s90, s14
	s_addc_u32 s15, s91, s15
	s_and_b64 s[16:17], s[12:13], exec
	s_cselect_b32 s1, s15, s19
	s_cselect_b32 s35, s14, s18
	s_ashr_i32 s11, s10, 31
	s_lshl_b64 s[16:17], s[10:11], 20
	s_add_u32 s16, s72, s16
	s_addc_u32 s17, s73, s17
	s_and_b64 s[22:23], s[12:13], exec
	s_cselect_b32 s11, s17, s21
	s_cselect_b32 s36, s16, s20
	s_add_u32 s18, s18, 0x80080
	s_addc_u32 s19, s19, 0
	s_add_u32 s37, s20, 0x100
	v_mov_b32_e32 v72, 0
	s_addc_u32 s38, s21, 0
	s_mov_b32 s39, -2
	v_mov_b32_e32 v73, v72
	v_mov_b32_e32 v74, v72
	v_mov_b32_e32 v75, v72
	v_mov_b32_e32 v84, v72
	v_mov_b32_e32 v85, v72
	v_mov_b32_e32 v86, v72
	v_mov_b32_e32 v87, v72
	v_mov_b32_e32 v88, v72
	v_mov_b32_e32 v89, v72
	v_mov_b32_e32 v90, v72
	v_mov_b32_e32 v91, v72
	v_mov_b32_e32 v100, v72
	v_mov_b32_e32 v101, v72
	v_mov_b32_e32 v102, v72
	v_mov_b32_e32 v103, v72
	v_mov_b32_e32 v104, v72
	v_mov_b32_e32 v105, v72
	v_mov_b32_e32 v106, v72
	v_mov_b32_e32 v107, v72
	v_mov_b32_e32 v116, v72
	v_mov_b32_e32 v117, v72
	v_mov_b32_e32 v118, v72
	v_mov_b32_e32 v119, v72
	v_mov_b32_e32 v120, v72
	v_mov_b32_e32 v121, v72
	v_mov_b32_e32 v122, v72
	v_mov_b32_e32 v123, v72
	v_mov_b32_e32 v76, v72
	v_mov_b32_e32 v77, v72
	v_mov_b32_e32 v78, v72
	v_mov_b32_e32 v79, v72
	v_mov_b32_e32 v80, v72
	v_mov_b32_e32 v81, v72
	v_mov_b32_e32 v82, v72
	v_mov_b32_e32 v83, v72
	v_mov_b32_e32 v92, v72
	v_mov_b32_e32 v93, v72
	v_mov_b32_e32 v94, v72
	v_mov_b32_e32 v95, v72
	v_mov_b32_e32 v96, v72
	v_mov_b32_e32 v97, v72
	v_mov_b32_e32 v98, v72
	v_mov_b32_e32 v99, v72
	v_mov_b32_e32 v108, v72
	v_mov_b32_e32 v109, v72
	v_mov_b32_e32 v110, v72
	v_mov_b32_e32 v111, v72
	v_mov_b32_e32 v112, v72
	v_mov_b32_e32 v113, v72
	v_mov_b32_e32 v114, v72
	v_mov_b32_e32 v115, v72
	v_mov_b32_e32 v124, v72
	v_mov_b32_e32 v125, v72
	v_mov_b32_e32 v126, v72
	v_mov_b32_e32 v127, v72
	v_mov_b32_e32 v128, v72
	v_mov_b32_e32 v129, v72
	v_mov_b32_e32 v130, v72
	v_mov_b32_e32 v131, v72
	v_mov_b32_e32 v68, v72
	v_mov_b32_e32 v69, v72
	v_mov_b32_e32 v70, v72
	v_mov_b32_e32 v71, v72
	v_mov_b32_e32 v64, v72
	v_mov_b32_e32 v65, v72
	v_mov_b32_e32 v66, v72
	v_mov_b32_e32 v67, v72
	v_mov_b32_e32 v60, v72
	v_mov_b32_e32 v61, v72
	v_mov_b32_e32 v62, v72
	v_mov_b32_e32 v63, v72
	v_mov_b32_e32 v48, v72
	v_mov_b32_e32 v49, v72
	v_mov_b32_e32 v50, v72
	v_mov_b32_e32 v51, v72
	v_mov_b32_e32 v44, v72
	v_mov_b32_e32 v45, v72
	v_mov_b32_e32 v46, v72
	v_mov_b32_e32 v47, v72
	v_mov_b32_e32 v32, v72
	v_mov_b32_e32 v33, v72
	v_mov_b32_e32 v34, v72
	v_mov_b32_e32 v35, v72
	v_mov_b32_e32 v28, v72
	v_mov_b32_e32 v29, v72
	v_mov_b32_e32 v30, v72
	v_mov_b32_e32 v31, v72
	v_mov_b32_e32 v16, v72
	v_mov_b32_e32 v17, v72
	v_mov_b32_e32 v18, v72
	v_mov_b32_e32 v19, v72
	v_mov_b32_e32 v12, v72
	v_mov_b32_e32 v13, v72
	v_mov_b32_e32 v14, v72
	v_mov_b32_e32 v15, v72
	v_mov_b32_e32 v56, v72
	v_mov_b32_e32 v57, v72
	v_mov_b32_e32 v58, v72
	v_mov_b32_e32 v59, v72
	v_mov_b32_e32 v52, v72
	v_mov_b32_e32 v53, v72
	v_mov_b32_e32 v54, v72
	v_mov_b32_e32 v55, v72
	v_mov_b32_e32 v40, v72
	v_mov_b32_e32 v41, v72
	v_mov_b32_e32 v42, v72
	v_mov_b32_e32 v43, v72
	v_mov_b32_e32 v36, v72
	v_mov_b32_e32 v37, v72
	v_mov_b32_e32 v38, v72
	v_mov_b32_e32 v39, v72
	v_mov_b32_e32 v24, v72
	v_mov_b32_e32 v25, v72
	v_mov_b32_e32 v26, v72
	v_mov_b32_e32 v27, v72
	v_mov_b32_e32 v20, v72
	v_mov_b32_e32 v21, v72
	v_mov_b32_e32 v22, v72
	v_mov_b32_e32 v23, v72
	v_mov_b32_e32 v8, v72
	v_mov_b32_e32 v9, v72
	v_mov_b32_e32 v10, v72
	v_mov_b32_e32 v11, v72
	v_mov_b32_e32 v4, v72
	v_mov_b32_e32 v5, v72
	v_mov_b32_e32 v6, v72
	v_mov_b32_e32 v7, v72
	.p2align 6

;     __device__ __forceinline__ bool next(int i, Unit& u) const { return decode(i * G + c, u); }
; template <class Epi, class Sched, bool DEFER>
; __device__ __forceinline__ void gemm_fast_core(LAS unsigned char* lds, const GemmP g, const Sched& S, const Epi& E, f32x4 (&acc)[2][2][4][2], Unit& cur) {
;     ...
;     for (;;) {
;         const bool has_next = S.next(ui + 1, nxt);
;         const char* nA = has_next ? (const char*)g.aptr(nxt) : cA; const char* nB = has_next ? (const char*)g.bptr(nxt) : cB;
;         for (int t = 0; t < nt; t += 2) {
;             const bool last = (t == nt - 2);
;             const char* a1 = cA + (size_t)(t + 1) * kstep;
;             const char* a2 = last ? nA : cA + (size_t)(t + 2) * kstep; const char* b2 = last ? nB : cB + (size_t)(t + 2) * kstep;
;     ...
;         for (int a = 0; a < 2; ++a)
; #pragma unroll
;             for (int b = 0; b < 2; ++b)
; #pragma unroll
;                 for (int m = 0; m < 4; ++m)
; #pragma unroll
;                     for (int n = 0; n < 2; ++n) acc[a][b][m][n] = (f32x4){0.f, 0.f, 0.f, 0.f};
.LBB0_1798:
	s_ashr_i32 s19, s18, 31
	s_lshl_b64 s[22:23], s[18:19], 20
	s_add_u32 s22, s90, s22
	s_addc_u32 s23, s91, s23
	s_and_b64 s[24:25], s[20:21], exec
	s_cselect_b32 s19, s23, s29
	s_cselect_b32 s47, s22, s28
	s_ashr_i32 s17, s16, 31
	s_lshl_b64 s[24:25], s[16:17], 20
	s_add_u32 s24, s96, s24
	s_addc_u32 s25, s97, s25
	s_and_b64 s[34:35], s[20:21], exec
	s_cselect_b32 s17, s25, s31
	s_cselect_b32 s48, s24, s30
	s_add_u32 s28, s28, 0x80080
	s_addc_u32 s29, s29, 0
	s_add_u32 s49, s30, 0x100
	v_mov_b32_e32 v0, 0
	s_addc_u32 s50, s31, 0
	s_mov_b32 s51, -2
	v_mov_b32_e32 v1, v0
	v_mov_b32_e32 v2, v0
	v_mov_b32_e32 v3, v0
	v_mov_b32_e32 v64, v0
	v_mov_b32_e32 v65, v0
	v_mov_b32_e32 v66, v0
	v_mov_b32_e32 v67, v0
	v_mov_b32_e32 v8, v0
	v_mov_b32_e32 v9, v0
	v_mov_b32_e32 v10, v0
	v_mov_b32_e32 v11, v0
	v_mov_b32_e32 v72, v0
	v_mov_b32_e32 v73, v0
	v_mov_b32_e32 v74, v0
	v_mov_b32_e32 v75, v0
	v_mov_b32_e32 v16, v0
	v_mov_b32_e32 v17, v0
	v_mov_b32_e32 v18, v0
	v_mov_b32_e32 v19, v0
	v_mov_b32_e32 v80, v0
	v_mov_b32_e32 v81, v0
	v_mov_b32_e32 v82, v0
	v_mov_b32_e32 v83, v0
	v_mov_b32_e32 v24, v0
	v_mov_b32_e32 v25, v0
	v_mov_b32_e32 v26, v0
	v_mov_b32_e32 v27, v0
	v_mov_b32_e32 v88, v0
	v_mov_b32_e32 v89, v0
	v_mov_b32_e32 v90, v0
	v_mov_b32_e32 v91, v0
	v_mov_b32_e32 v4, v0
	v_mov_b32_e32 v5, v0
	v_mov_b32_e32 v6, v0
	v_mov_b32_e32 v7, v0
	v_mov_b32_e32 v68, v0
	v_mov_b32_e32 v69, v0
	v_mov_b32_e32 v70, v0
	v_mov_b32_e32 v71, v0
	v_mov_b32_e32 v12, v0
	v_mov_b32_e32 v13, v0
	v_mov_b32_e32 v14, v0
	v_mov_b32_e32 v15, v0
	v_mov_b32_e32 v76, v0
	v_mov_b32_e32 v77, v0
	v_mov_b32_e32 v78, v0
	v_mov_b32_e32 v79, v0
	v_mov_b32_e32 v20, v0
	v_mov_b32_e32 v21, v0
	v_mov_b32_e32 v22, v0
	v_mov_b32_e32 v23, v0
	v_mov_b32_e32 v84, v0
	v_mov_b32_e32 v85, v0
	v_mov_b32_e32 v86, v0
	v_mov_b32_e32 v87, v0
	v_mov_b32_e32 v28, v0
	v_mov_b32_e32 v29, v0
	v_mov_b32_e32 v30, v0
	v_mov_b32_e32 v31, v0
	v_mov_b32_e32 v92, v0
	v_mov_b32_e32 v93, v0
	v_mov_b32_e32 v94, v0
	v_mov_b32_e32 v95, v0
	v_mov_b32_e32 v32, v0
	v_mov_b32_e32 v33, v0
	v_mov_b32_e32 v34, v0
	v_mov_b32_e32 v35, v0
	v_mov_b32_e32 v96, v0
	v_mov_b32_e32 v97, v0
	v_mov_b32_e32 v98, v0
	v_mov_b32_e32 v99, v0
	v_mov_b32_e32 v40, v0
	v_mov_b32_e32 v41, v0
	v_mov_b32_e32 v42, v0
	v_mov_b32_e32 v43, v0
	v_mov_b32_e32 v104, v0
	v_mov_b32_e32 v105, v0
	v_mov_b32_e32 v106, v0
	v_mov_b32_e32 v107, v0
	v_mov_b32_e32 v48, v0
	v_mov_b32_e32 v49, v0
	v_mov_b32_e32 v50, v0
	v_mov_b32_e32 v51, v0
	v_mov_b32_e32 v112, v0
	v_mov_b32_e32 v113, v0
	v_mov_b32_e32 v114, v0
	v_mov_b32_e32 v115, v0
	v_mov_b32_e32 v56, v0
	v_mov_b32_e32 v57, v0
	v_mov_b32_e32 v58, v0
	v_mov_b32_e32 v59, v0
	v_mov_b32_e32 v152, v0
	v_mov_b32_e32 v153, v0
	v_mov_b32_e32 v154, v0
	v_mov_b32_e32 v155, v0
	v_mov_b32_e32 v36, v0
	v_mov_b32_e32 v37, v0
	v_mov_b32_e32 v38, v0
	v_mov_b32_e32 v39, v0
	v_mov_b32_e32 v100, v0
	v_mov_b32_e32 v101, v0
	v_mov_b32_e32 v102, v0
	v_mov_b32_e32 v103, v0
	v_mov_b32_e32 v44, v0
	v_mov_b32_e32 v45, v0
	v_mov_b32_e32 v46, v0
	v_mov_b32_e32 v47, v0
	v_mov_b32_e32 v108, v0
	v_mov_b32_e32 v109, v0
	v_mov_b32_e32 v110, v0
	v_mov_b32_e32 v111, v0
	v_mov_b32_e32 v52, v0
	v_mov_b32_e32 v53, v0
	v_mov_b32_e32 v54, v0
	v_mov_b32_e32 v55, v0
	v_mov_b32_e32 v116, v0
	v_mov_b32_e32 v117, v0
	v_mov_b32_e32 v118, v0
	v_mov_b32_e32 v119, v0
	v_mov_b32_e32 v60, v0
	v_mov_b32_e32 v61, v0
	v_mov_b32_e32 v62, v0
	v_mov_b32_e32 v63, v0
	v_mov_b32_e32 v156, v0
	v_mov_b32_e32 v157, v0
	v_mov_b32_e32 v158, v0
	v_mov_b32_e32 v159, v0
	.p2align 6

; __device__ __forceinline__ void st_bf4(bf16_t* p, f32x4 v) { u32x2 w; w.x = pk2(v[0], v[1]); w.y = pk2(v[2], v[3]); *(u32x2*)p = w; }
; __device__ __forceinline__ float sigmoidf_(float x) { return __builtin_amdgcn_rcpf(1.f + __expf(-x)); }
; __device__ __forceinline__ float dpp_ror1(float v) { return __int_as_float(__builtin_amdgcn_update_dpp(0, __float_as_int(v), 0x121, 0xf, 0xf, false)); }
; __device__ __forceinline__ float dpp_rol1(float v) { return __int_as_float(__builtin_amdgcn_update_dpp(0, __float_as_int(v), 0x12F, 0xf, 0xf, false)); }
;     __device__ __forceinline__ void tile(const f32x4 (&acc)[2][2][4][2], const Unit& u, int wr, int wc, int fr, int fq) const {
; #pragma unroll
;         for (int n = 0; n < 2; ++n) {
;             const int cv = 128 * u.pn + 32 * wc + 16 * n + 4 * fq, cg = FF + cv;
;             const f32x4 wv0 = *(const f32x4*)(cw + cv), wv1 = *(const f32x4*)(cw + F2 + cv), wv2 = *(const f32x4*)(cw + 2 * F2 + cv), bv = *(const f32x4*)(cb + cv);
;             const f32x4 wg0 = *(const f32x4*)(cw + cg), wg1 = *(const f32x4*)(cw + F2 + cg), wg2 = *(const f32x4*)(cw + 2 * F2 + cg), bg = *(const f32x4*)(cb + cg);
; #pragma unroll
;             for (int ai = 0; ai < 2; ++ai)
; #pragma unroll
;                 for (int m = 0; m < 4; ++m) {
;                     f32x4 r;
; #pragma unroll
;                     for (int i = 0; i < 4; ++i) {
;                         const float xv = acc[ai][0][m][n][i], xg = acc[ai][1][m][n][i];
;                         const float uv = m > 0 ? acc[ai][0][m > 0 ? m - 1 : 0][n][i] : 0.f, ug = m > 0 ? acc[ai][1][m > 0 ? m - 1 : 0][n][i] : 0.f;
;                         const float dv = m < 3 ? acc[ai][0][m < 3 ? m + 1 : 3][n][i] : 0.f, dg = m < 3 ? acc[ai][1][m < 3 ? m + 1 : 3][n][i] : 0.f;
;                         const float pv = dpp_ror1(fr == 15 ? uv : xv), pg = dpp_ror1(fr == 15 ? ug : xg);
;                         const float nv = dpp_rol1(fr == 0 ? dv : xv), ng = dpp_rol1(fr == 0 ? dg : xg);
;                         const float yv = wv0[i] * pv + wv1[i] * xv + wv2[i] * nv + bv[i];
;                         const float yg = wg0[i] * pg + wg1[i] * xg + wg2[i] * ng + bg[i];
;                         r[i] = yg * sigmoidf_(yg) * yv;
;                     }
;                     st_bf4(ACT + (size_t)(u.pm * BM + ai * HALF + wr * 64 + m * 16 + fr) * FF + cv, r);
;                 }
.LBB0_1802:
	v_lshl_or_b32 v170, s33, 7, v204
	v_ashrrev_i32_e32 v171, 31, v170
	v_lshlrev_b64 v[120:121], 2, v[170:171]
	v_lshl_add_u64 v[172:173], s[56:57], 0, v[120:121]
	v_add_co_u32_e32 v176, vcc, 0x5000, v172
	v_lshl_add_u64 v[122:123], s[12:13], 0, v[120:121]
	s_nop 0
	v_addc_co_u32_e32 v177, vcc, 0, v173, vcc
	v_add_co_u32_e32 v178, vcc, 0x5000, v122
	v_lshl_add_u64 v[124:125], s[14:15], 0, v[120:121]
	s_nop 0
	v_addc_co_u32_e32 v179, vcc, 0, v123, vcc
	global_load_dwordx4 v[132:135], v[176:177], off offset:2048
	global_load_dwordx4 v[148:151], v[178:179], off offset:2048
	v_add_co_u32_e32 v180, vcc, 0x5000, v124
	v_lshl_add_u64 v[174:175], s[58:59], 0, v[120:121]
	s_nop 0
	v_addc_co_u32_e32 v181, vcc, 0, v125, vcc
	global_load_dwordx4 v[136:139], v[180:181], off offset:2048
	v_add_co_u32_e32 v182, vcc, 0x5000, v174
	v_cndmask_b32_e64 v168, v156, 0, s[4:5]
	s_nop 0
	v_addc_co_u32_e32 v183, vcc, 0, v175, vcc
	global_load_dwordx4 v[140:143], v[182:183], off offset:2048
	global_load_dwordx4 v[144:147], v[122:123], off
	s_nop 0
	global_load_dwordx4 v[120:123], v[172:173], off
	s_nop 0
	global_load_dwordx4 v[124:127], v[124:125], off
	s_nop 0
	global_load_dwordx4 v[128:131], v[174:175], off
	v_cndmask_b32_e64 v169, v152, 0, s[4:5]
	v_mov_b32_dpp v208, v168 row_ror:1 row_mask:0xf bank_mask:0xf
	s_nop 0
	v_mov_b32_dpp v168, v169 row_ror:1 row_mask:0xf bank_mask:0xf
	v_cndmask_b32_e64 v169, v156, v116, s[6:7]
	v_cndmask_b32_e64 v184, v153, 0, s[4:5]
	s_nop 0
	v_mov_b32_dpp v210, v169 row_ror:15 row_mask:0xf bank_mask:0xf
	v_cndmask_b32_e64 v169, v152, v112, s[6:7]
	s_nop 1
	v_mov_b32_dpp v186, v169 row_ror:15 row_mask:0xf bank_mask:0xf
	v_cndmask_b32_e64 v169, v157, 0, s[4:5]
	s_nop 1
	v_mov_b32_dpp v209, v169 row_ror:1 row_mask:0xf bank_mask:0xf
	v_mov_b32_dpp v169, v184 row_ror:1 row_mask:0xf bank_mask:0xf
	v_cndmask_b32_e64 v184, v157, v117, s[6:7]
	s_nop 1
	v_mov_b32_dpp v211, v184 row_ror:15 row_mask:0xf bank_mask:0xf
	v_cndmask_b32_e64 v184, v153, v113, s[6:7]
	s_lshl_b32 s17, s26, 8
	s_nop 0
	v_mov_b32_dpp v187, v184 row_ror:15 row_mask:0xf bank_mask:0xf
	v_cndmask_b32_e64 v184, v158, 0, s[4:5]
	v_add_u32_e32 v220, s17, v195
	s_andn2_b64 vcc, exec, s[20:21]
	v_mov_b32_dpp v212, v184 row_ror:1 row_mask:0xf bank_mask:0xf
	v_cndmask_b32_e64 v184, v154, 0, s[4:5]
	s_mov_b64 s[20:21], -1
	s_waitcnt vmcnt(0)
	v_pk_mul_f32 v[222:223], v[152:153], v[148:149]
	s_nop 0
	v_pk_fma_f32 v[168:169], v[132:133], v[168:169], v[222:223]
	v_mov_b32_dpp v214, v184 row_ror:1 row_mask:0xf bank_mask:0xf
	v_cndmask_b32_e64 v184, v158, v118, s[6:7]
	v_pk_fma_f32 v[168:169], v[136:137], v[186:187], v[168:169]
	v_lshlrev_b64 v[186:187], 1, v[170:171]
	v_pk_add_f32 v[222:223], v[140:141], v[168:169]
	v_mov_b32_dpp v216, v184 row_ror:15 row_mask:0xf bank_mask:0xf
	v_mul_f32_e32 v168, 0xbfb8aa3b, v222
	v_exp_f32_e32 v224, v168
	v_cndmask_b32_e64 v184, v154, v114, s[6:7]
	v_pk_mul_f32 v[228:229], v[156:157], v[144:145]
	v_pk_mul_f32 v[226:227], v[158:159], v[146:147]
	v_add_f32_e32 v171, 1.0, v224
	v_mul_f32_e32 v224, 0xbfb8aa3b, v223
	v_exp_f32_e32 v225, v224
	v_mov_b32_dpp v218, v184 row_ror:15 row_mask:0xf bank_mask:0xf
	v_cndmask_b32_e64 v184, v159, 0, s[4:5]
	v_rcp_f32_e32 v224, v171
	v_add_f32_e32 v171, 1.0, v225
	v_mov_b32_dpp v213, v184 row_ror:1 row_mask:0xf bank_mask:0xf
	v_cndmask_b32_e64 v184, v155, 0, s[4:5]
	v_rcp_f32_e32 v225, v171
	v_pk_fma_f32 v[208:209], v[120:121], v[208:209], v[228:229]
	v_mov_b32_dpp v215, v184 row_ror:1 row_mask:0xf bank_mask:0xf
	v_cndmask_b32_e64 v184, v159, v119, s[6:7]
	v_pk_fma_f32 v[208:209], v[124:125], v[210:211], v[208:209]
	v_pk_mul_f32 v[210:211], v[222:223], v[224:225]
	v_mov_b32_dpp v217, v184 row_ror:15 row_mask:0xf bank_mask:0xf
	v_cndmask_b32_e64 v184, v155, v115, s[6:7]
	v_pk_add_f32 v[208:209], v[128:129], v[208:209]
	v_pk_fma_f32 v[212:213], v[122:123], v[212:213], v[226:227]
	v_mov_b32_dpp v219, v184 row_ror:15 row_mask:0xf bank_mask:0xf
	v_mov_b64_e32 v[184:185], s[0:1]
	v_mad_i64_i32 v[220:221], s[28:29], v220, s46, v[184:185]
	v_lshl_add_u64 v[168:169], v[220:221], 0, v[186:187]
	v_pk_mul_f32 v[220:221], v[154:155], v[150:151]
	v_pk_mul_f32 v[208:209], v[208:209], v[210:211]
	v_pk_fma_f32 v[210:211], v[134:135], v[214:215], v[220:221]
	v_pk_fma_f32 v[212:213], v[126:127], v[216:217], v[212:213]
	v_pk_fma_f32 v[210:211], v[138:139], v[218:219], v[210:211]
	v_pk_add_f32 v[212:213], v[130:131], v[212:213]
	v_pk_add_f32 v[210:211], v[142:143], v[210:211]
	v_cvt_pk_bf16_f32 v208, v208, v209
	v_mul_f32_e32 v171, 0xbfb8aa3b, v210
	v_exp_f32_e32 v171, v171
	v_mul_f32_e32 v214, 0xbfb8aa3b, v211
	v_exp_f32_e32 v215, v214
	v_pk_mul_f32 v[216:217], v[112:113], v[148:149]
	v_add_f32_e32 v171, 1.0, v171
	v_rcp_f32_e32 v214, v171
	v_add_f32_e32 v171, 1.0, v215
	v_rcp_f32_e32 v215, v171
	v_cndmask_b32_e64 v171, v116, v156, s[4:5]
	v_pk_mul_f32 v[222:223], v[116:117], v[144:145]
	v_pk_mul_f32 v[210:211], v[210:211], v[214:215]
	v_mov_b32_dpp v156, v171 row_ror:1 row_mask:0xf bank_mask:0xf
	v_pk_mul_f32 v[210:211], v[212:213], v[210:211]
	v_cndmask_b32_e64 v171, v112, v152, s[4:5]
	v_cvt_pk_bf16_f32 v209, v210, v211
	global_store_dwordx2 v[168:169], v[208:209], off
	v_mov_b32_dpp v152, v171 row_ror:1 row_mask:0xf bank_mask:0xf
	v_cndmask_b32_e64 v171, v116, v108, s[6:7]
	s_nop 1
	v_mov_b32_dpp v208, v171 row_ror:15 row_mask:0xf bank_mask:0xf
	v_cndmask_b32_e64 v171, v112, v104, s[6:7]
	s_nop 1
	v_mov_b32_dpp v210, v171 row_ror:15 row_mask:0xf bank_mask:0xf
	v_cndmask_b32_e64 v171, v117, v157, s[4:5]
	s_nop 1
	v_mov_b32_dpp v157, v171 row_ror:1 row_mask:0xf bank_mask:0xf
	v_cndmask_b32_e64 v171, v113, v153, s[4:5]
; __device__ __forceinline__ void st_bf4(bf16_t* p, f32x4 v) { u32x2 w; w.x = pk2(v[0], v[1]); w.y = pk2(v[2], v[3]); *(u32x2*)p = w; }
; __device__ __forceinline__ float sigmoidf_(float x) { return __builtin_amdgcn_rcpf(1.f + __expf(-x)); }
; __device__ __forceinline__ float dpp_ror1(float v) { return __int_as_float(__builtin_amdgcn_update_dpp(0, __float_as_int(v), 0x121, 0xf, 0xf, false)); }
; __device__ __forceinline__ float dpp_rol1(float v) { return __int_as_float(__builtin_amdgcn_update_dpp(0, __float_as_int(v), 0x12F, 0xf, 0xf, false)); }
;     __device__ __forceinline__ void tile(const f32x4 (&acc)[2][2][4][2], const Unit& u, int wr, int wc, int fr, int fq) const {
;     ...
;             const int cv = 128 * u.pn + 32 * wc + 16 * n + 4 * fq, cg = FF + cv;
;             const f32x4 wv0 = *(const f32x4*)(cw + cv), wv1 = *(const f32x4*)(cw + F2 + cv), wv2 = *(const f32x4*)(cw + 2 * F2 + cv), bv = *(const f32x4*)(cb + cv);
;             const f32x4 wg0 = *(const f32x4*)(cw + cg), wg1 = *(const f32x4*)(cw + F2 + cg), wg2 = *(const f32x4*)(cw + 2 * F2 + cg), bg = *(const f32x4*)(cb + cg);
; #pragma unroll
;             for (int ai = 0; ai < 2; ++ai)
; #pragma unroll
;                 for (int m = 0; m < 4; ++m) {
;                     f32x4 r;
; #pragma unroll
;                     for (int i = 0; i < 4; ++i) {
;                         const float xv = acc[ai][0][m][n][i], xg = acc[ai][1][m][n][i];
;                         const float uv = m > 0 ? acc[ai][0][m > 0 ? m - 1 : 0][n][i] : 0.f, ug = m > 0 ? acc[ai][1][m > 0 ? m - 1 : 0][n][i] : 0.f;
;                         const float dv = m < 3 ? acc[ai][0][m < 3 ? m + 1 : 3][n][i] : 0.f, dg = m < 3 ? acc[ai][1][m < 3 ? m + 1 : 3][n][i] : 0.f;
;                         const float pv = dpp_ror1(fr == 15 ? uv : xv), pg = dpp_ror1(fr == 15 ? ug : xg);
;                         const float nv = dpp_rol1(fr == 0 ? dv : xv), ng = dpp_rol1(fr == 0 ? dg : xg);
;                         const float yv = wv0[i] * pv + wv1[i] * xv + wv2[i] * nv + bv[i];
;                         const float yg = wg0[i] * pg + wg1[i] * xg + wg2[i] * ng + bg[i];
;                         r[i] = yg * sigmoidf_(yg) * yv;
;                     }
;                     st_bf4(ACT + (size_t)(u.pm * BM + ai * HALF + wr * 64 + m * 16 + fr) * FF + cv, r);
	v_pk_fma_f32 v[156:157], v[120:121], v[156:157], v[222:223]
	s_nop 0
	v_mov_b32_dpp v153, v171 row_ror:1 row_mask:0xf bank_mask:0xf
	v_cndmask_b32_e64 v171, v117, v109, s[6:7]
	v_pk_fma_f32 v[152:153], v[132:133], v[152:153], v[216:217]
	v_pk_mul_f32 v[216:217], v[114:115], v[150:151]
	v_mov_b32_dpp v209, v171 row_ror:15 row_mask:0xf bank_mask:0xf
	v_cndmask_b32_e64 v171, v113, v105, s[6:7]
	v_pk_fma_f32 v[156:157], v[124:125], v[208:209], v[156:157]
	v_pk_mul_f32 v[220:221], v[118:119], v[146:147]
	v_mov_b32_dpp v211, v171 row_ror:15 row_mask:0xf bank_mask:0xf
	v_cndmask_b32_e64 v171, v118, v158, s[4:5]
	v_pk_fma_f32 v[152:153], v[136:137], v[210:211], v[152:153]
	v_pk_add_f32 v[156:157], v[128:129], v[156:157]
	v_mov_b32_dpp v158, v171 row_ror:1 row_mask:0xf bank_mask:0xf
	v_cndmask_b32_e64 v171, v114, v154, s[4:5]
	v_pk_add_f32 v[210:211], v[140:141], v[152:153]
	s_nop 0
	v_mov_b32_dpp v154, v171 row_ror:1 row_mask:0xf bank_mask:0xf
	v_cndmask_b32_e64 v171, v118, v110, s[6:7]
	v_mul_f32_e32 v152, 0xbfb8aa3b, v210
	v_exp_f32_e32 v218, v152
	v_mov_b32_dpp v212, v171 row_ror:15 row_mask:0xf bank_mask:0xf
	v_cndmask_b32_e64 v171, v114, v106, s[6:7]
	s_nop 1
	v_mov_b32_dpp v214, v171 row_ror:15 row_mask:0xf bank_mask:0xf
	v_cndmask_b32_e64 v171, v119, v159, s[4:5]
	s_nop 1
	v_mov_b32_dpp v159, v171 row_ror:1 row_mask:0xf bank_mask:0xf
	v_cndmask_b32_e64 v171, v115, v155, s[4:5]
	v_pk_fma_f32 v[158:159], v[122:123], v[158:159], v[220:221]
	s_nop 0
	v_mov_b32_dpp v155, v171 row_ror:1 row_mask:0xf bank_mask:0xf
	v_cndmask_b32_e64 v171, v119, v111, s[6:7]
	v_pk_fma_f32 v[154:155], v[134:135], v[154:155], v[216:217]
	v_pk_mul_f32 v[216:217], v[108:109], v[144:145]
	v_mov_b32_dpp v213, v171 row_ror:15 row_mask:0xf bank_mask:0xf
	v_cndmask_b32_e64 v171, v115, v107, s[6:7]
	v_pk_fma_f32 v[158:159], v[126:127], v[212:213], v[158:159]
	s_nop 0
	v_mov_b32_dpp v215, v171 row_ror:15 row_mask:0xf bank_mask:0xf
	v_add_u32_e32 v171, s17, v197
	v_mad_i64_i32 v[152:153], s[28:29], v171, s46, v[184:185]
	v_add_f32_e32 v171, 1.0, v218
	v_mul_f32_e32 v218, 0xbfb8aa3b, v211
	v_exp_f32_e32 v219, v218
	v_rcp_f32_e32 v218, v171
	v_pk_fma_f32 v[154:155], v[138:139], v[214:215], v[154:155]
	v_pk_add_f32 v[158:159], v[130:131], v[158:159]
	v_add_f32_e32 v171, 1.0, v219
	v_rcp_f32_e32 v219, v171
	v_pk_add_f32 v[154:155], v[142:143], v[154:155]
	v_lshl_add_u64 v[152:153], v[152:153], 0, v[186:187]
	v_mul_f32_e32 v171, 0xbfb8aa3b, v154
	v_pk_mul_f32 v[208:209], v[210:211], v[218:219]
	v_exp_f32_e32 v171, v171
	v_pk_mul_f32 v[156:157], v[156:157], v[208:209]
	v_mul_f32_e32 v208, 0xbfb8aa3b, v155
	v_exp_f32_e32 v209, v208
	v_cvt_pk_bf16_f32 v156, v156, v157
	v_add_f32_e32 v157, 1.0, v171
	v_rcp_f32_e32 v208, v157
	v_add_f32_e32 v157, 1.0, v209
	v_rcp_f32_e32 v209, v157
	v_pk_mul_f32 v[210:211], v[104:105], v[148:149]
	v_cndmask_b32_e64 v171, v111, v103, s[6:7]
	v_pk_mul_f32 v[214:215], v[110:111], v[146:147]
	v_pk_mul_f32 v[154:155], v[154:155], v[208:209]
	s_nop 0
	v_pk_mul_f32 v[154:155], v[158:159], v[154:155]
	v_cndmask_b32_e64 v158, v105, v97, s[6:7]
	v_cvt_pk_bf16_f32 v157, v154, v155
	v_cndmask_b32_e64 v154, v108, v116, s[4:5]
	v_cndmask_b32_e64 v155, v108, v100, s[6:7]
	global_store_dwordx2 v[152:153], v[156:157], off
	v_mov_b32_dpp v116, v154 row_ror:1 row_mask:0xf bank_mask:0xf
	v_cndmask_b32_e64 v154, v104, v112, s[4:5]
	v_cndmask_b32_e64 v157, v109, v101, s[6:7]
	s_nop 0
	v_mov_b32_dpp v112, v154 row_ror:1 row_mask:0xf bank_mask:0xf
	v_cndmask_b32_e64 v159, v110, v102, s[6:7]
	v_mov_b32_dpp v154, v155 row_ror:15 row_mask:0xf bank_mask:0xf
	v_cndmask_b32_e64 v155, v104, v96, s[6:7]
	s_nop 1
	v_mov_b32_dpp v156, v155 row_ror:15 row_mask:0xf bank_mask:0xf
	v_cndmask_b32_e64 v155, v109, v117, s[4:5]
	s_nop 1
	v_mov_b32_dpp v117, v155 row_ror:1 row_mask:0xf bank_mask:0xf
	v_cndmask_b32_e64 v155, v105, v113, s[4:5]
	v_pk_fma_f32 v[116:117], v[120:121], v[116:117], v[216:217]
	s_nop 0
	v_mov_b32_dpp v113, v155 row_ror:1 row_mask:0xf bank_mask:0xf
	v_pk_fma_f32 v[112:113], v[132:133], v[112:113], v[210:211]
	v_pk_mul_f32 v[210:211], v[106:107], v[150:151]
	v_mov_b32_dpp v155, v157 row_ror:15 row_mask:0xf bank_mask:0xf
	v_pk_fma_f32 v[116:117], v[124:125], v[154:155], v[116:117]
	s_nop 0
	v_mov_b32_dpp v157, v158 row_ror:15 row_mask:0xf bank_mask:0xf
	v_cndmask_b32_e64 v158, v110, v118, s[4:5]
	v_pk_fma_f32 v[112:113], v[136:137], v[156:157], v[112:113]
	v_pk_add_f32 v[116:117], v[128:129], v[116:117]
	v_mov_b32_dpp v118, v158 row_ror:1 row_mask:0xf bank_mask:0xf
	v_cndmask_b32_e64 v158, v106, v114, s[4:5]
	v_pk_add_f32 v[156:157], v[140:141], v[112:113]
	s_nop 0
	v_mov_b32_dpp v114, v158 row_ror:1 row_mask:0xf bank_mask:0xf
	v_mul_f32_e32 v112, 0xbfb8aa3b, v156
	v_exp_f32_e32 v212, v112
	v_mov_b32_dpp v158, v159 row_ror:15 row_mask:0xf bank_mask:0xf
	v_cndmask_b32_e64 v159, v106, v98, s[6:7]
	s_nop 1
	v_mov_b32_dpp v208, v159 row_ror:15 row_mask:0xf bank_mask:0xf
	v_cndmask_b32_e64 v159, v111, v119, s[4:5]
	s_nop 1
	v_mov_b32_dpp v119, v159 row_ror:1 row_mask:0xf bank_mask:0xf
	v_cndmask_b32_e64 v159, v107, v115, s[4:5]
	v_pk_fma_f32 v[118:119], v[122:123], v[118:119], v[214:215]
	s_nop 0
	v_mov_b32_dpp v115, v159 row_ror:1 row_mask:0xf bank_mask:0xf
	v_pk_fma_f32 v[114:115], v[134:135], v[114:115], v[210:211]
	s_nop 0
	v_mov_b32_dpp v159, v171 row_ror:15 row_mask:0xf bank_mask:0xf
	v_cndmask_b32_e64 v171, v107, v99, s[6:7]
	v_pk_fma_f32 v[118:119], v[126:127], v[158:159], v[118:119]
	s_nop 0
	v_mov_b32_dpp v209, v171 row_ror:15 row_mask:0xf bank_mask:0xf
	v_add_u32_e32 v171, s17, v198
	v_mad_i64_i32 v[112:113], s[28:29], v171, s46, v[184:185]
	v_add_f32_e32 v171, 1.0, v212
; __device__ __forceinline__ void st_bf4(bf16_t* p, f32x4 v) { u32x2 w; w.x = pk2(v[0], v[1]); w.y = pk2(v[2], v[3]); *(u32x2*)p = w; }
; __device__ __forceinline__ float sigmoidf_(float x) { return __builtin_amdgcn_rcpf(1.f + __expf(-x)); }
; __device__ __forceinline__ float dpp_ror1(float v) { return __int_as_float(__builtin_amdgcn_update_dpp(0, __float_as_int(v), 0x121, 0xf, 0xf, false)); }
; __device__ __forceinline__ float dpp_rol1(float v) { return __int_as_float(__builtin_amdgcn_update_dpp(0, __float_as_int(v), 0x12F, 0xf, 0xf, false)); }
;     __device__ __forceinline__ void tile(const f32x4 (&acc)[2][2][4][2], const Unit& u, int wr, int wc, int fr, int fq) const {
;     ...
;                     for (int i = 0; i < 4; ++i) {
;                         const float xv = acc[ai][0][m][n][i], xg = acc[ai][1][m][n][i];
;                         const float uv = m > 0 ? acc[ai][0][m > 0 ? m - 1 : 0][n][i] : 0.f, ug = m > 0 ? acc[ai][1][m > 0 ? m - 1 : 0][n][i] : 0.f;
;                         const float dv = m < 3 ? acc[ai][0][m < 3 ? m + 1 : 3][n][i] : 0.f, dg = m < 3 ? acc[ai][1][m < 3 ? m + 1 : 3][n][i] : 0.f;
;                         const float pv = dpp_ror1(fr == 15 ? uv : xv), pg = dpp_ror1(fr == 15 ? ug : xg);
;                         const float nv = dpp_rol1(fr == 0 ? dv : xv), ng = dpp_rol1(fr == 0 ? dg : xg);
;                         const float yv = wv0[i] * pv + wv1[i] * xv + wv2[i] * nv + bv[i];
;                         const float yg = wg0[i] * pg + wg1[i] * xg + wg2[i] * ng + bg[i];
;                         r[i] = yg * sigmoidf_(yg) * yv;
;                     }
;                     st_bf4(ACT + (size_t)(u.pm * BM + ai * HALF + wr * 64 + m * 16 + fr) * FF + cv, r);
	v_mul_f32_e32 v212, 0xbfb8aa3b, v157
	v_exp_f32_e32 v213, v212
	v_rcp_f32_e32 v212, v171
	v_pk_fma_f32 v[114:115], v[138:139], v[208:209], v[114:115]
	v_pk_add_f32 v[118:119], v[130:131], v[118:119]
	v_add_f32_e32 v171, 1.0, v213
	v_rcp_f32_e32 v213, v171
	v_pk_add_f32 v[114:115], v[142:143], v[114:115]
	v_lshl_add_u64 v[112:113], v[112:113], 0, v[186:187]
	v_pk_mul_f32 v[154:155], v[156:157], v[212:213]
	s_nop 0
	v_pk_mul_f32 v[116:117], v[116:117], v[154:155]
	v_mul_f32_e32 v154, 0xbfb8aa3b, v114
	v_exp_f32_e32 v154, v154
	v_mul_f32_e32 v155, 0xbfb8aa3b, v115
	v_exp_f32_e32 v155, v155
	v_cvt_pk_bf16_f32 v116, v116, v117
	v_add_f32_e32 v117, 1.0, v154
	v_rcp_f32_e32 v154, v117
	v_add_f32_e32 v117, 1.0, v155
	v_rcp_f32_e32 v155, v117
	v_cndmask_b32_e64 v156, v99, 0, s[6:7]
	v_pk_mul_f32 v[114:115], v[114:115], v[154:155]
	s_nop 0
	v_pk_mul_f32 v[114:115], v[118:119], v[114:115]
	v_cndmask_b32_e64 v118, v97, 0, s[6:7]
	v_cvt_pk_bf16_f32 v117, v114, v115
	v_cndmask_b32_e64 v114, v100, v108, s[4:5]
	v_cndmask_b32_e64 v115, v100, 0, s[6:7]
	global_store_dwordx2 v[112:113], v[116:117], off
	v_mov_b32_dpp v108, v114 row_ror:1 row_mask:0xf bank_mask:0xf
	v_cndmask_b32_e64 v114, v96, v104, s[4:5]
	v_cndmask_b32_e64 v117, v101, 0, s[6:7]
	s_nop 0
	v_mov_b32_dpp v104, v114 row_ror:1 row_mask:0xf bank_mask:0xf
	v_cndmask_b32_e64 v119, v102, 0, s[6:7]
	v_mov_b32_dpp v114, v115 row_ror:15 row_mask:0xf bank_mask:0xf
	v_cndmask_b32_e64 v115, v96, 0, s[6:7]
	v_cndmask_b32_e64 v155, v103, 0, s[6:7]
	s_nop 0
	v_mov_b32_dpp v116, v115 row_ror:15 row_mask:0xf bank_mask:0xf
	v_cndmask_b32_e64 v115, v101, v109, s[4:5]
	v_pk_mul_f32 v[100:101], v[100:101], v[144:145]
	s_nop 0
	v_mov_b32_dpp v109, v115 row_ror:1 row_mask:0xf bank_mask:0xf
	v_cndmask_b32_e64 v115, v97, v105, s[4:5]
	v_pk_mul_f32 v[96:97], v[96:97], v[148:149]
	v_pk_fma_f32 v[100:101], v[120:121], v[108:109], v[100:101]
	v_mov_b32_dpp v105, v115 row_ror:1 row_mask:0xf bank_mask:0xf
	v_pk_fma_f32 v[96:97], v[132:133], v[104:105], v[96:97]
	v_mov_b32_dpp v115, v117 row_ror:15 row_mask:0xf bank_mask:0xf
	v_pk_fma_f32 v[100:101], v[124:125], v[114:115], v[100:101]
	v_mov_b32_dpp v117, v118 row_ror:15 row_mask:0xf bank_mask:0xf
	v_pk_fma_f32 v[96:97], v[136:137], v[116:117], v[96:97]
	v_cndmask_b32_e64 v118, v102, v110, s[4:5]
	v_pk_add_f32 v[104:105], v[140:141], v[96:97]
	s_nop 0
	v_mul_f32_e32 v96, 0xbfb8aa3b, v104
	v_mul_f32_e32 v117, 0xbfb8aa3b, v105
	v_mov_b32_dpp v110, v118 row_ror:1 row_mask:0xf bank_mask:0xf
	v_cndmask_b32_e64 v118, v98, v106, s[4:5]
	v_exp_f32_e32 v116, v96
	v_exp_f32_e32 v117, v117
	v_mov_b32_dpp v106, v118 row_ror:1 row_mask:0xf bank_mask:0xf
	v_add_f32_e32 v116, 1.0, v116
	v_add_f32_e32 v117, 1.0, v117
	v_mov_b32_dpp v118, v119 row_ror:15 row_mask:0xf bank_mask:0xf
	v_cndmask_b32_e64 v119, v98, 0, s[6:7]
	v_rcp_f32_e32 v116, v116
	v_rcp_f32_e32 v117, v117
	v_mov_b32_dpp v154, v119 row_ror:15 row_mask:0xf bank_mask:0xf
	v_cndmask_b32_e64 v119, v103, v111, s[4:5]
	v_pk_add_f32 v[100:101], v[128:129], v[100:101]
	v_pk_mul_f32 v[104:105], v[104:105], v[116:117]
	v_mov_b32_dpp v111, v119 row_ror:1 row_mask:0xf bank_mask:0xf
	v_cndmask_b32_e64 v119, v99, v107, s[4:5]
	v_pk_mul_f32 v[98:99], v[98:99], v[150:151]
	v_pk_mul_f32 v[100:101], v[100:101], v[104:105]
	v_mov_b32_dpp v107, v119 row_ror:1 row_mask:0xf bank_mask:0xf
	v_pk_fma_f32 v[98:99], v[134:135], v[106:107], v[98:99]
	v_cvt_pk_bf16_f32 v100, v100, v101
	v_mov_b32_dpp v119, v155 row_ror:15 row_mask:0xf bank_mask:0xf
	v_pk_mul_f32 v[102:103], v[102:103], v[146:147]
	v_cndmask_b32_e64 v106, v89, v81, s[6:7]
	v_mov_b32_dpp v155, v156 row_ror:15 row_mask:0xf bank_mask:0xf
	v_pk_fma_f32 v[98:99], v[138:139], v[154:155], v[98:99]
	v_pk_fma_f32 v[102:103], v[122:123], v[110:111], v[102:103]
	v_pk_add_f32 v[98:99], v[142:143], v[98:99]
	v_pk_fma_f32 v[102:103], v[126:127], v[118:119], v[102:103]
	v_mul_f32_e32 v104, 0xbfb8aa3b, v98
	v_exp_f32_e32 v104, v104
	v_mul_f32_e32 v105, 0xbfb8aa3b, v99
	v_exp_f32_e32 v105, v105
	v_add_u32_e32 v156, s17, v199
	v_add_f32_e32 v101, 1.0, v104
	v_rcp_f32_e32 v104, v101
	v_add_f32_e32 v101, 1.0, v105
	v_rcp_f32_e32 v105, v101
	v_pk_add_f32 v[102:103], v[130:131], v[102:103]
	v_mad_i64_i32 v[96:97], s[28:29], v156, s46, v[184:185]
	v_pk_mul_f32 v[98:99], v[98:99], v[104:105]
	v_lshl_add_u64 v[96:97], v[96:97], 0, v[186:187]
	v_pk_mul_f32 v[98:99], v[102:103], v[98:99]
	s_nop 0
	v_cvt_pk_bf16_f32 v101, v98, v99
	global_store_dwordx2 v[96:97], v[100:101], off
	v_cndmask_b32_e64 v98, v92, 0, s[4:5]
	v_cndmask_b32_e64 v99, v88, 0, s[4:5]
	s_nop 0
	v_mov_b32_dpp v100, v98 row_ror:1 row_mask:0xf bank_mask:0xf
	v_cndmask_b32_e64 v103, v89, 0, s[4:5]
	v_mov_b32_dpp v98, v99 row_ror:1 row_mask:0xf bank_mask:0xf
	v_cndmask_b32_e64 v99, v92, v84, s[6:7]
	v_cndmask_b32_e64 v105, v93, v85, s[6:7]
	v_cndmask_b32_e64 v107, v94, 0, s[4:5]
	v_mov_b32_dpp v102, v99 row_ror:15 row_mask:0xf bank_mask:0xf
	v_cndmask_b32_e64 v99, v88, v80, s[6:7]
	v_cndmask_b32_e64 v109, v95, 0, s[4:5]
	s_nop 0
	v_mov_b32_dpp v104, v99 row_ror:15 row_mask:0xf bank_mask:0xf
	v_cndmask_b32_e64 v99, v93, 0, s[4:5]
	v_cndmask_b32_e64 v111, v91, 0, s[4:5]
	v_cndmask_b32_e64 v115, v95, v87, s[6:7]
	v_mov_b32_dpp v101, v99 row_ror:1 row_mask:0xf bank_mask:0xf
	v_cndmask_b32_e64 v116, v91, v83, s[6:7]
	v_add_u32_e32 v118, s17, v200
	v_mov_b32_dpp v99, v103 row_ror:1 row_mask:0xf bank_mask:0xf
	v_pk_mul_f32 v[156:157], v[92:93], v[144:145]
	v_pk_mul_f32 v[154:155], v[94:95], v[146:147]
	v_mov_b32_dpp v103, v105 row_ror:15 row_mask:0xf bank_mask:0xf
	v_pk_fma_f32 v[100:101], v[120:121], v[100:101], v[156:157]
	s_nop 0
; __device__ __forceinline__ void st_bf4(bf16_t* p, f32x4 v) { u32x2 w; w.x = pk2(v[0], v[1]); w.y = pk2(v[2], v[3]); *(u32x2*)p = w; }
; __device__ __forceinline__ float sigmoidf_(float x) { return __builtin_amdgcn_rcpf(1.f + __expf(-x)); }
; __device__ __forceinline__ float dpp_ror1(float v) { return __int_as_float(__builtin_amdgcn_update_dpp(0, __float_as_int(v), 0x121, 0xf, 0xf, false)); }
; __device__ __forceinline__ float dpp_rol1(float v) { return __int_as_float(__builtin_amdgcn_update_dpp(0, __float_as_int(v), 0x12F, 0xf, 0xf, false)); }
;     __device__ __forceinline__ void tile(const f32x4 (&acc)[2][2][4][2], const Unit& u, int wr, int wc, int fr, int fq) const {
;     ...
;                     for (int i = 0; i < 4; ++i) {
;                         const float xv = acc[ai][0][m][n][i], xg = acc[ai][1][m][n][i];
;                         const float uv = m > 0 ? acc[ai][0][m > 0 ? m - 1 : 0][n][i] : 0.f, ug = m > 0 ? acc[ai][1][m > 0 ? m - 1 : 0][n][i] : 0.f;
;                         const float dv = m < 3 ? acc[ai][0][m < 3 ? m + 1 : 3][n][i] : 0.f, dg = m < 3 ? acc[ai][1][m < 3 ? m + 1 : 3][n][i] : 0.f;
;                         const float pv = dpp_ror1(fr == 15 ? uv : xv), pg = dpp_ror1(fr == 15 ? ug : xg);
;                         const float nv = dpp_rol1(fr == 0 ? dv : xv), ng = dpp_rol1(fr == 0 ? dg : xg);
;                         const float yv = wv0[i] * pv + wv1[i] * xv + wv2[i] * nv + bv[i];
;                         const float yg = wg0[i] * pg + wg1[i] * xg + wg2[i] * ng + bg[i];
;                         r[i] = yg * sigmoidf_(yg) * yv;
;                     }
;                     st_bf4(ACT + (size_t)(u.pm * BM + ai * HALF + wr * 64 + m * 16 + fr) * FF + cv, r);
	v_mov_b32_dpp v105, v106 row_ror:15 row_mask:0xf bank_mask:0xf
	v_pk_fma_f32 v[100:101], v[124:125], v[102:103], v[100:101]
	s_nop 0
	v_mov_b32_dpp v106, v107 row_ror:1 row_mask:0xf bank_mask:0xf
	v_cndmask_b32_e64 v107, v90, 0, s[4:5]
	v_pk_add_f32 v[100:101], v[128:129], v[100:101]
	s_nop 0
	v_mov_b32_dpp v108, v107 row_ror:1 row_mask:0xf bank_mask:0xf
	v_cndmask_b32_e64 v107, v94, v86, s[6:7]
	s_nop 1
	v_mov_b32_dpp v110, v107 row_ror:15 row_mask:0xf bank_mask:0xf
	v_cndmask_b32_e64 v107, v90, v82, s[6:7]
	s_nop 1
	v_mov_b32_dpp v114, v107 row_ror:15 row_mask:0xf bank_mask:0xf
	s_nop 1
	v_mov_b32_dpp v107, v109 row_ror:1 row_mask:0xf bank_mask:0xf
	v_pk_fma_f32 v[106:107], v[122:123], v[106:107], v[154:155]
	s_nop 0
	v_mov_b32_dpp v109, v111 row_ror:1 row_mask:0xf bank_mask:0xf
	s_nop 1
	v_mov_b32_dpp v111, v115 row_ror:15 row_mask:0xf bank_mask:0xf
	v_pk_fma_f32 v[106:107], v[126:127], v[110:111], v[106:107]
	v_add_u32_e32 v110, s17, v201
	v_mov_b32_dpp v115, v116 row_ror:15 row_mask:0xf bank_mask:0xf
	v_pk_mul_f32 v[116:117], v[88:89], v[148:149]
	v_pk_add_f32 v[106:107], v[130:131], v[106:107]
	v_pk_fma_f32 v[98:99], v[132:133], v[98:99], v[116:117]
	v_pk_mul_f32 v[116:117], v[90:91], v[150:151]
	v_pk_fma_f32 v[98:99], v[136:137], v[104:105], v[98:99]
	s_nop 0
	v_pk_add_f32 v[104:105], v[140:141], v[98:99]
	s_nop 0
	v_mul_f32_e32 v98, 0xbfb8aa3b, v104
	v_exp_f32_e32 v119, v98
	v_mad_i64_i32 v[98:99], s[28:29], v118, s46, v[184:185]
	v_lshl_add_u64 v[98:99], v[98:99], 0, v[186:187]
	v_add_f32_e32 v118, 1.0, v119
	v_mul_f32_e32 v119, 0xbfb8aa3b, v105
	v_exp_f32_e32 v119, v119
	v_rcp_f32_e32 v118, v118
	v_add_f32_e32 v119, 1.0, v119
	v_rcp_f32_e32 v119, v119
	s_nop 0
	v_pk_mul_f32 v[102:103], v[104:105], v[118:119]
	s_nop 0
	v_pk_mul_f32 v[100:101], v[100:101], v[102:103]
	v_pk_fma_f32 v[102:103], v[134:135], v[108:109], v[116:117]
	v_cvt_pk_bf16_f32 v100, v100, v101
	v_pk_fma_f32 v[102:103], v[138:139], v[114:115], v[102:103]
	v_cndmask_b32_e64 v108, v83, v75, s[6:7]
	v_pk_add_f32 v[102:103], v[142:143], v[102:103]
	v_pk_mul_f32 v[116:117], v[84:85], v[144:145]
	v_mul_f32_e32 v104, 0xbfb8aa3b, v102
	v_exp_f32_e32 v104, v104
	v_mul_f32_e32 v105, 0xbfb8aa3b, v103
	v_exp_f32_e32 v105, v105
	v_pk_mul_f32 v[114:115], v[86:87], v[146:147]
	v_add_f32_e32 v101, 1.0, v104
	v_rcp_f32_e32 v104, v101
	v_add_f32_e32 v101, 1.0, v105
	v_rcp_f32_e32 v105, v101
	v_cndmask_b32_e64 v119, v63, 0, s[4:5]
	v_pk_mul_f32 v[102:103], v[102:103], v[104:105]
	s_nop 0
	v_pk_mul_f32 v[102:103], v[106:107], v[102:103]
	v_cndmask_b32_e64 v104, v81, v73, s[6:7]
	v_cvt_pk_bf16_f32 v101, v102, v103
	global_store_dwordx2 v[98:99], v[100:101], off
	v_cndmask_b32_e64 v100, v84, v92, s[4:5]
	v_cndmask_b32_e64 v101, v80, v72, s[6:7]
	s_nop 0
	v_mov_b32_dpp v92, v100 row_ror:1 row_mask:0xf bank_mask:0xf
	v_cndmask_b32_e64 v100, v80, v88, s[4:5]
	v_cndmask_b32_e64 v105, v86, v78, s[6:7]
	s_nop 0
	v_mov_b32_dpp v88, v100 row_ror:1 row_mask:0xf bank_mask:0xf
	v_cndmask_b32_e64 v100, v84, v76, s[6:7]
	v_cndmask_b32_e64 v107, v87, v79, s[6:7]
	s_nop 0
	v_mov_b32_dpp v102, v100 row_ror:15 row_mask:0xf bank_mask:0xf
	s_nop 1
	v_mov_b32_dpp v100, v101 row_ror:15 row_mask:0xf bank_mask:0xf
	v_cndmask_b32_e64 v101, v85, v93, s[4:5]
	s_nop 1
	v_mov_b32_dpp v93, v101 row_ror:1 row_mask:0xf bank_mask:0xf
	v_cndmask_b32_e64 v101, v81, v89, s[4:5]
	v_pk_fma_f32 v[92:93], v[120:121], v[92:93], v[116:117]
	v_cndmask_b32_e64 v116, v57, v49, s[6:7]
	v_mov_b32_dpp v89, v101 row_ror:1 row_mask:0xf bank_mask:0xf
	v_cndmask_b32_e64 v101, v85, v77, s[6:7]
	v_cndmask_b32_e64 v117, v62, 0, s[4:5]
	s_nop 0
	v_mov_b32_dpp v103, v101 row_ror:15 row_mask:0xf bank_mask:0xf
	v_pk_fma_f32 v[92:93], v[124:125], v[102:103], v[92:93]
	v_cndmask_b32_e64 v102, v75, v67, s[6:7]
	v_mov_b32_dpp v101, v104 row_ror:15 row_mask:0xf bank_mask:0xf
	v_cndmask_b32_e64 v104, v86, v94, s[4:5]
	v_pk_add_f32 v[92:93], v[128:129], v[92:93]
	s_nop 0
	v_mov_b32_dpp v94, v104 row_ror:1 row_mask:0xf bank_mask:0xf
	v_cndmask_b32_e64 v104, v82, v90, s[4:5]
	s_nop 1
	v_mov_b32_dpp v90, v104 row_ror:1 row_mask:0xf bank_mask:0xf
	s_nop 1
	v_mov_b32_dpp v104, v105 row_ror:15 row_mask:0xf bank_mask:0xf
	v_cndmask_b32_e64 v105, v82, v74, s[6:7]
	s_nop 1
	v_mov_b32_dpp v106, v105 row_ror:15 row_mask:0xf bank_mask:0xf
	v_cndmask_b32_e64 v105, v87, v95, s[4:5]
	s_nop 1
	v_mov_b32_dpp v95, v105 row_ror:1 row_mask:0xf bank_mask:0xf
	v_cndmask_b32_e64 v105, v83, v91, s[4:5]
	v_pk_fma_f32 v[94:95], v[122:123], v[94:95], v[114:115]
	s_nop 0
	v_mov_b32_dpp v91, v105 row_ror:1 row_mask:0xf bank_mask:0xf
	v_cndmask_b32_e64 v115, v61, v53, s[6:7]
	s_nop 0
	v_mov_b32_dpp v105, v107 row_ror:15 row_mask:0xf bank_mask:0xf
	v_pk_fma_f32 v[94:95], v[126:127], v[104:105], v[94:95]
	v_add_u32_e32 v104, s17, v202
	v_mov_b32_dpp v107, v108 row_ror:15 row_mask:0xf bank_mask:0xf
	v_pk_mul_f32 v[108:109], v[80:81], v[148:149]
	v_pk_add_f32 v[94:95], v[130:131], v[94:95]
	v_pk_fma_f32 v[88:89], v[132:133], v[88:89], v[108:109]
	v_pk_mul_f32 v[108:109], v[82:83], v[150:151]
	v_pk_fma_f32 v[88:89], v[136:137], v[100:101], v[88:89]
	v_pk_fma_f32 v[90:91], v[134:135], v[90:91], v[108:109]
	v_pk_add_f32 v[88:89], v[140:141], v[88:89]
	v_pk_fma_f32 v[90:91], v[138:139], v[106:107], v[90:91]
	v_mul_f32_e32 v100, 0xbfb8aa3b, v88
	v_exp_f32_e32 v111, v100
	v_mad_i64_i32 v[100:101], s[28:29], v110, s46, v[184:185]
	v_pk_add_f32 v[90:91], v[142:143], v[90:91]
	v_add_f32_e32 v110, 1.0, v111
	v_mul_f32_e32 v111, 0xbfb8aa3b, v89
	v_exp_f32_e32 v111, v111
	v_rcp_f32_e32 v110, v110
	v_lshl_add_u64 v[100:101], v[100:101], 0, v[186:187]
	v_pk_mul_f32 v[108:109], v[76:77], v[144:145]
; __device__ __forceinline__ void st_bf4(bf16_t* p, f32x4 v) { u32x2 w; w.x = pk2(v[0], v[1]); w.y = pk2(v[2], v[3]); *(u32x2*)p = w; }
; __device__ __forceinline__ float sigmoidf_(float x) { return __builtin_amdgcn_rcpf(1.f + __expf(-x)); }
; __device__ __forceinline__ float dpp_ror1(float v) { return __int_as_float(__builtin_amdgcn_update_dpp(0, __float_as_int(v), 0x121, 0xf, 0xf, false)); }
; __device__ __forceinline__ float dpp_rol1(float v) { return __int_as_float(__builtin_amdgcn_update_dpp(0, __float_as_int(v), 0x12F, 0xf, 0xf, false)); }
;     __device__ __forceinline__ void tile(const f32x4 (&acc)[2][2][4][2], const Unit& u, int wr, int wc, int fr, int fq) const {
;     ...
;                     for (int i = 0; i < 4; ++i) {
;                         const float xv = acc[ai][0][m][n][i], xg = acc[ai][1][m][n][i];
;                         const float uv = m > 0 ? acc[ai][0][m > 0 ? m - 1 : 0][n][i] : 0.f, ug = m > 0 ? acc[ai][1][m > 0 ? m - 1 : 0][n][i] : 0.f;
;                         const float dv = m < 3 ? acc[ai][0][m < 3 ? m + 1 : 3][n][i] : 0.f, dg = m < 3 ? acc[ai][1][m < 3 ? m + 1 : 3][n][i] : 0.f;
;                         const float pv = dpp_ror1(fr == 15 ? uv : xv), pg = dpp_ror1(fr == 15 ? ug : xg);
;                         const float nv = dpp_rol1(fr == 0 ? dv : xv), ng = dpp_rol1(fr == 0 ? dg : xg);
;                         const float yv = wv0[i] * pv + wv1[i] * xv + wv2[i] * nv + bv[i];
;                         const float yg = wg0[i] * pg + wg1[i] * xg + wg2[i] * ng + bg[i];
;                         r[i] = yg * sigmoidf_(yg) * yv;
;                     }
;                     st_bf4(ACT + (size_t)(u.pm * BM + ai * HALF + wr * 64 + m * 16 + fr) * FF + cv, r);
	v_add_f32_e32 v111, 1.0, v111
	v_rcp_f32_e32 v111, v111
	v_pk_mul_f32 v[106:107], v[78:79], v[146:147]
	v_pk_mul_f32 v[88:89], v[88:89], v[110:111]
	s_nop 0
	v_pk_mul_f32 v[88:89], v[92:93], v[88:89]
	v_mul_f32_e32 v92, 0xbfb8aa3b, v90
	v_exp_f32_e32 v92, v92
	v_mul_f32_e32 v93, 0xbfb8aa3b, v91
	v_exp_f32_e32 v93, v93
	v_cvt_pk_bf16_f32 v88, v88, v89
	v_add_f32_e32 v89, 1.0, v92
	v_rcp_f32_e32 v92, v89
	v_add_f32_e32 v89, 1.0, v93
	v_rcp_f32_e32 v93, v89
	v_cndmask_b32_e64 v111, v57, 0, s[4:5]
	v_pk_mul_f32 v[90:91], v[90:91], v[92:93]
	s_nop 0
	v_pk_mul_f32 v[90:91], v[94:95], v[90:91]
	v_cndmask_b32_e64 v92, v73, v65, s[6:7]
	v_cvt_pk_bf16_f32 v89, v90, v91
	global_store_dwordx2 v[100:101], v[88:89], off
	v_cndmask_b32_e64 v88, v76, v84, s[4:5]
	v_cndmask_b32_e64 v89, v76, v68, s[6:7]
	s_nop 0
	v_mov_b32_dpp v84, v88 row_ror:1 row_mask:0xf bank_mask:0xf
	v_cndmask_b32_e64 v88, v72, v80, s[4:5]
	v_cndmask_b32_e64 v91, v77, v69, s[6:7]
	v_cndmask_b32_e64 v93, v78, v70, s[6:7]
	v_mov_b32_dpp v80, v88 row_ror:1 row_mask:0xf bank_mask:0xf
	v_cndmask_b32_e64 v95, v79, v71, s[6:7]
	v_mov_b32_dpp v88, v89 row_ror:15 row_mask:0xf bank_mask:0xf
	v_cndmask_b32_e64 v89, v72, v64, s[6:7]
	s_nop 1
	v_mov_b32_dpp v90, v89 row_ror:15 row_mask:0xf bank_mask:0xf
	v_cndmask_b32_e64 v89, v77, v85, s[4:5]
	s_nop 1
	v_mov_b32_dpp v85, v89 row_ror:1 row_mask:0xf bank_mask:0xf
	v_cndmask_b32_e64 v89, v73, v81, s[4:5]
	v_pk_fma_f32 v[84:85], v[120:121], v[84:85], v[108:109]
	s_nop 0
	v_mov_b32_dpp v81, v89 row_ror:1 row_mask:0xf bank_mask:0xf
	v_cndmask_b32_e64 v109, v61, 0, s[4:5]
	s_nop 0
	v_mov_b32_dpp v89, v91 row_ror:15 row_mask:0xf bank_mask:0xf
	v_pk_fma_f32 v[84:85], v[124:125], v[88:89], v[84:85]
	v_cndmask_b32_e64 v88, v67, 0, s[6:7]
	v_mov_b32_dpp v91, v92 row_ror:15 row_mask:0xf bank_mask:0xf
	v_cndmask_b32_e64 v92, v78, v86, s[4:5]
	v_pk_add_f32 v[84:85], v[128:129], v[84:85]
	s_nop 0
	v_mov_b32_dpp v86, v92 row_ror:1 row_mask:0xf bank_mask:0xf
	v_cndmask_b32_e64 v92, v74, v82, s[4:5]
	s_nop 1
	v_mov_b32_dpp v82, v92 row_ror:1 row_mask:0xf bank_mask:0xf
	s_nop 1
	v_mov_b32_dpp v92, v93 row_ror:15 row_mask:0xf bank_mask:0xf
	v_cndmask_b32_e64 v93, v74, v66, s[6:7]
	s_nop 1
	v_mov_b32_dpp v94, v93 row_ror:15 row_mask:0xf bank_mask:0xf
	v_cndmask_b32_e64 v93, v79, v87, s[4:5]
	s_nop 1
	v_mov_b32_dpp v87, v93 row_ror:1 row_mask:0xf bank_mask:0xf
	v_cndmask_b32_e64 v93, v75, v83, s[4:5]
	v_pk_fma_f32 v[86:87], v[122:123], v[86:87], v[106:107]
	v_cndmask_b32_e64 v107, v60, 0, s[4:5]
	v_mov_b32_dpp v83, v93 row_ror:1 row_mask:0xf bank_mask:0xf
	s_nop 0
	v_mov_b32_dpp v93, v95 row_ror:15 row_mask:0xf bank_mask:0xf
	v_pk_fma_f32 v[86:87], v[126:127], v[92:93], v[86:87]
	v_mov_b32_dpp v106, v107 row_ror:1 row_mask:0xf bank_mask:0xf
	v_mov_b32_dpp v95, v102 row_ror:15 row_mask:0xf bank_mask:0xf
	v_pk_mul_f32 v[102:103], v[72:73], v[148:149]
	v_pk_add_f32 v[86:87], v[130:131], v[86:87]
	v_pk_fma_f32 v[80:81], v[132:133], v[80:81], v[102:103]
	v_cndmask_b32_e64 v107, v56, 0, s[4:5]
	v_pk_fma_f32 v[80:81], v[136:137], v[90:91], v[80:81]
	s_nop 0
	v_pk_add_f32 v[80:81], v[140:141], v[80:81]
	v_mov_b32_dpp v108, v107 row_ror:1 row_mask:0xf bank_mask:0xf
	v_mul_f32_e32 v90, 0xbfb8aa3b, v80
	v_exp_f32_e32 v105, v90
	v_mad_i64_i32 v[90:91], s[28:29], v104, s46, v[184:185]
	v_lshl_add_u64 v[102:103], v[90:91], 0, v[186:187]
	v_add_f32_e32 v104, 1.0, v105
	v_mul_f32_e32 v105, 0xbfb8aa3b, v81
	v_exp_f32_e32 v105, v105
	v_rcp_f32_e32 v104, v104
	v_pk_mul_f32 v[90:91], v[74:75], v[150:151]
	v_cndmask_b32_e64 v107, v60, v52, s[6:7]
	v_add_f32_e32 v105, 1.0, v105
	v_rcp_f32_e32 v105, v105
	v_pk_fma_f32 v[82:83], v[134:135], v[82:83], v[90:91]
	v_mov_b32_dpp v110, v107 row_ror:15 row_mask:0xf bank_mask:0xf
	v_pk_fma_f32 v[82:83], v[138:139], v[94:95], v[82:83]
	v_pk_mul_f32 v[80:81], v[80:81], v[104:105]
	v_pk_add_f32 v[82:83], v[142:143], v[82:83]
	v_pk_mul_f32 v[80:81], v[84:85], v[80:81]
	v_mul_f32_e32 v84, 0xbfb8aa3b, v82
	v_exp_f32_e32 v84, v84
	v_mul_f32_e32 v85, 0xbfb8aa3b, v83
	v_exp_f32_e32 v85, v85
	v_cvt_pk_bf16_f32 v80, v80, v81
	v_add_f32_e32 v81, 1.0, v84
	v_rcp_f32_e32 v84, v81
	v_add_f32_e32 v81, 1.0, v85
	v_rcp_f32_e32 v85, v81
	v_cndmask_b32_e64 v107, v56, v48, s[6:7]
	v_pk_mul_f32 v[82:83], v[82:83], v[84:85]
	s_nop 0
	v_pk_mul_f32 v[82:83], v[86:87], v[82:83]
	v_cndmask_b32_e64 v84, v65, 0, s[6:7]
	v_cvt_pk_bf16_f32 v81, v82, v83
	global_store_dwordx2 v[102:103], v[80:81], off
	v_cndmask_b32_e64 v80, v68, v76, s[4:5]
	v_cndmask_b32_e64 v81, v68, 0, s[6:7]
	s_nop 0
	v_mov_b32_dpp v76, v80 row_ror:1 row_mask:0xf bank_mask:0xf
	v_cndmask_b32_e64 v80, v64, v72, s[4:5]
	v_cndmask_b32_e64 v83, v69, 0, s[6:7]
	v_cndmask_b32_e64 v85, v70, 0, s[6:7]
	v_mov_b32_dpp v72, v80 row_ror:1 row_mask:0xf bank_mask:0xf
	v_cndmask_b32_e64 v87, v71, 0, s[6:7]
	v_mov_b32_dpp v80, v81 row_ror:15 row_mask:0xf bank_mask:0xf
	v_cndmask_b32_e64 v81, v64, 0, s[6:7]
	v_mov_b32_dpp v114, v107 row_ror:15 row_mask:0xf bank_mask:0xf
	s_nop 0
	v_mov_b32_dpp v82, v81 row_ror:15 row_mask:0xf bank_mask:0xf
	v_cndmask_b32_e64 v81, v69, v77, s[4:5]
	v_pk_mul_f32 v[68:69], v[68:69], v[144:145]
	v_mov_b32_dpp v107, v109 row_ror:1 row_mask:0xf bank_mask:0xf
	v_mov_b32_dpp v77, v81 row_ror:1 row_mask:0xf bank_mask:0xf
	v_cndmask_b32_e64 v81, v65, v73, s[4:5]
	v_pk_mul_f32 v[64:65], v[64:65], v[148:149]
	v_pk_fma_f32 v[68:69], v[120:121], v[76:77], v[68:69]
	v_mov_b32_dpp v73, v81 row_ror:1 row_mask:0xf bank_mask:0xf
	v_pk_fma_f32 v[64:65], v[132:133], v[72:73], v[64:65]
	v_mov_b32_dpp v81, v83 row_ror:15 row_mask:0xf bank_mask:0xf
	v_pk_fma_f32 v[68:69], v[124:125], v[80:81], v[68:69]
; __device__ __forceinline__ void st_bf4(bf16_t* p, f32x4 v) { u32x2 w; w.x = pk2(v[0], v[1]); w.y = pk2(v[2], v[3]); *(u32x2*)p = w; }
; __device__ __forceinline__ float sigmoidf_(float x) { return __builtin_amdgcn_rcpf(1.f + __expf(-x)); }
; __device__ __forceinline__ float dpp_ror1(float v) { return __int_as_float(__builtin_amdgcn_update_dpp(0, __float_as_int(v), 0x121, 0xf, 0xf, false)); }
; __device__ __forceinline__ float dpp_rol1(float v) { return __int_as_float(__builtin_amdgcn_update_dpp(0, __float_as_int(v), 0x12F, 0xf, 0xf, false)); }
;     __device__ __forceinline__ void tile(const f32x4 (&acc)[2][2][4][2], const Unit& u, int wr, int wc, int fr, int fq) const {
;     ...
;             const f32x4 wv0 = *(const f32x4*)(cw + cv), wv1 = *(const f32x4*)(cw + F2 + cv), wv2 = *(const f32x4*)(cw + 2 * F2 + cv), bv = *(const f32x4*)(cb + cv);
;             const f32x4 wg0 = *(const f32x4*)(cw + cg), wg1 = *(const f32x4*)(cw + F2 + cg), wg2 = *(const f32x4*)(cw + 2 * F2 + cg), bg = *(const f32x4*)(cb + cg);
; #pragma unroll
;             for (int ai = 0; ai < 2; ++ai)
; #pragma unroll
;                 for (int m = 0; m < 4; ++m) {
;                     f32x4 r;
; #pragma unroll
;                     for (int i = 0; i < 4; ++i) {
;                         const float xv = acc[ai][0][m][n][i], xg = acc[ai][1][m][n][i];
;                         const float uv = m > 0 ? acc[ai][0][m > 0 ? m - 1 : 0][n][i] : 0.f, ug = m > 0 ? acc[ai][1][m > 0 ? m - 1 : 0][n][i] : 0.f;
;                         const float dv = m < 3 ? acc[ai][0][m < 3 ? m + 1 : 3][n][i] : 0.f, dg = m < 3 ? acc[ai][1][m < 3 ? m + 1 : 3][n][i] : 0.f;
;                         const float pv = dpp_ror1(fr == 15 ? uv : xv), pg = dpp_ror1(fr == 15 ? ug : xg);
;                         const float nv = dpp_rol1(fr == 0 ? dv : xv), ng = dpp_rol1(fr == 0 ? dg : xg);
;                         const float yv = wv0[i] * pv + wv1[i] * xv + wv2[i] * nv + bv[i];
;                         const float yg = wg0[i] * pg + wg1[i] * xg + wg2[i] * ng + bg[i];
;                         r[i] = yg * sigmoidf_(yg) * yv;
;                     }
;                     st_bf4(ACT + (size_t)(u.pm * BM + ai * HALF + wr * 64 + m * 16 + fr) * FF + cv, r);
	v_mov_b32_dpp v109, v111 row_ror:1 row_mask:0xf bank_mask:0xf
	v_mov_b32_dpp v83, v84 row_ror:15 row_mask:0xf bank_mask:0xf
	v_cndmask_b32_e64 v84, v70, v78, s[4:5]
	v_pk_fma_f32 v[64:65], v[136:137], v[82:83], v[64:65]
	v_pk_add_f32 v[68:69], v[128:129], v[68:69]
	v_mov_b32_dpp v78, v84 row_ror:1 row_mask:0xf bank_mask:0xf
	v_cndmask_b32_e64 v84, v66, v74, s[4:5]
	v_pk_add_f32 v[64:65], v[140:141], v[64:65]
	s_nop 0
	v_mov_b32_dpp v74, v84 row_ror:1 row_mask:0xf bank_mask:0xf
	v_mul_f32_e32 v72, 0xbfb8aa3b, v64
	v_exp_f32_e32 v82, v72
	v_mov_b32_dpp v84, v85 row_ror:15 row_mask:0xf bank_mask:0xf
	v_cndmask_b32_e64 v85, v66, 0, s[6:7]
	v_mov_b32_dpp v111, v115 row_ror:15 row_mask:0xf bank_mask:0xf
	s_nop 0
	v_mov_b32_dpp v86, v85 row_ror:15 row_mask:0xf bank_mask:0xf
	v_cndmask_b32_e64 v85, v71, v79, s[4:5]
	v_pk_mul_f32 v[70:71], v[70:71], v[146:147]
	v_mov_b32_dpp v115, v116 row_ror:15 row_mask:0xf bank_mask:0xf
	v_mov_b32_dpp v79, v85 row_ror:1 row_mask:0xf bank_mask:0xf
	v_cndmask_b32_e64 v85, v67, v75, s[4:5]
	v_pk_mul_f32 v[66:67], v[66:67], v[150:151]
	v_pk_fma_f32 v[70:71], v[122:123], v[78:79], v[70:71]
	v_mov_b32_dpp v75, v85 row_ror:1 row_mask:0xf bank_mask:0xf
	v_pk_fma_f32 v[66:67], v[134:135], v[74:75], v[66:67]
	v_mov_b32_dpp v85, v87 row_ror:15 row_mask:0xf bank_mask:0xf
	v_pk_fma_f32 v[70:71], v[126:127], v[84:85], v[70:71]
	v_mov_b32_dpp v116, v117 row_ror:1 row_mask:0xf bank_mask:0xf
	v_mov_b32_dpp v87, v88 row_ror:15 row_mask:0xf bank_mask:0xf
	v_add_u32_e32 v88, s17, v203
	v_mad_i64_i32 v[72:73], s[28:29], v88, s46, v[184:185]
	v_lshl_add_u64 v[104:105], v[72:73], 0, v[186:187]
	v_mul_f32_e32 v73, 0xbfb8aa3b, v65
	v_exp_f32_e32 v73, v73
	v_add_f32_e32 v72, 1.0, v82
	v_rcp_f32_e32 v72, v72
	v_pk_fma_f32 v[66:67], v[138:139], v[86:87], v[66:67]
	v_add_f32_e32 v73, 1.0, v73
	v_rcp_f32_e32 v73, v73
	v_pk_add_f32 v[66:67], v[142:143], v[66:67]
	v_pk_add_f32 v[70:71], v[130:131], v[70:71]
	v_cndmask_b32_e64 v117, v58, 0, s[4:5]
	v_pk_mul_f32 v[64:65], v[64:65], v[72:73]
	s_nop 0
	v_pk_mul_f32 v[64:65], v[68:69], v[64:65]
	v_mul_f32_e32 v68, 0xbfb8aa3b, v66
	v_exp_f32_e32 v68, v68
	v_mul_f32_e32 v69, 0xbfb8aa3b, v67
	v_exp_f32_e32 v69, v69
	v_cvt_pk_bf16_f32 v64, v64, v65
	v_add_f32_e32 v65, 1.0, v68
	v_rcp_f32_e32 v68, v65
	v_add_f32_e32 v65, 1.0, v69
	v_rcp_f32_e32 v69, v65
	v_mov_b32_dpp v118, v117 row_ror:1 row_mask:0xf bank_mask:0xf
	v_cndmask_b32_e64 v117, v62, v54, s[6:7]
	v_pk_mul_f32 v[66:67], v[66:67], v[68:69]
	s_nop 0
	v_mov_b32_dpp v120, v117 row_ror:15 row_mask:0xf bank_mask:0xf
	v_pk_mul_f32 v[66:67], v[70:71], v[66:67]
	v_cndmask_b32_e64 v117, v58, v50, s[6:7]
	v_cvt_pk_bf16_f32 v65, v66, v67
	global_store_dwordx2 v[104:105], v[64:65], off
	global_load_dwordx4 v[92:95], v[178:179], off offset:2112
	global_load_dwordx4 v[76:79], v[176:177], off offset:2112
	global_load_dwordx4 v[80:83], v[180:181], off offset:2112
	global_load_dwordx4 v[84:87], v[182:183], off offset:2112
	v_or_b32_e32 v64, 16, v170
	v_ashrrev_i32_e32 v65, 31, v64
	v_lshlrev_b64 v[68:69], 2, v[64:65]
	v_lshl_add_u64 v[64:65], s[12:13], 0, v[68:69]
	global_load_dwordx4 v[88:91], v[64:65], off
	s_nop 0
	global_load_dwordx4 v[64:67], v[172:173], off offset:64
	v_lshl_add_u64 v[68:69], s[14:15], 0, v[68:69]
	global_load_dwordx4 v[68:71], v[68:69], off
	s_nop 0
	global_load_dwordx4 v[72:75], v[174:175], off offset:64
	v_mov_b32_dpp v122, v117 row_ror:15 row_mask:0xf bank_mask:0xf
	v_cndmask_b32_e64 v121, v59, 0, s[4:5]
	v_cndmask_b32_e64 v123, v63, v55, s[6:7]
	v_mov_b32_dpp v117, v119 row_ror:1 row_mask:0xf bank_mask:0xf
	v_cndmask_b32_e64 v126, v59, v51, s[6:7]
	s_waitcnt vmcnt(7)
	v_pk_mul_f32 v[124:125], v[56:57], v[92:93]
	s_waitcnt vmcnt(6)
	v_pk_fma_f32 v[108:109], v[76:77], v[108:109], v[124:125]
	v_mov_b32_dpp v119, v121 row_ror:1 row_mask:0xf bank_mask:0xf
	s_waitcnt vmcnt(5)
	v_pk_fma_f32 v[108:109], v[80:81], v[114:115], v[108:109]
	s_waitcnt vmcnt(4)
	v_pk_add_f32 v[108:109], v[84:85], v[108:109]
	s_waitcnt vmcnt(3)
	v_pk_mul_f32 v[128:129], v[60:61], v[88:89]
	v_mul_f32_e32 v114, 0xbfb8aa3b, v108
	v_mul_f32_e32 v125, 0xbfb8aa3b, v109
	v_exp_f32_e32 v124, v114
	v_exp_f32_e32 v125, v125
	s_waitcnt vmcnt(2)
	v_pk_fma_f32 v[106:107], v[64:65], v[106:107], v[128:129]
	v_mov_b32_dpp v121, v123 row_ror:15 row_mask:0xf bank_mask:0xf
	v_add_f32_e32 v124, 1.0, v124
	v_add_f32_e32 v125, 1.0, v125
	v_rcp_f32_e32 v124, v124
	v_rcp_f32_e32 v125, v125
	s_waitcnt vmcnt(1)
	v_pk_fma_f32 v[106:107], v[68:69], v[110:111], v[106:107]
	v_pk_mul_f32 v[114:115], v[58:59], v[94:95]
	s_waitcnt vmcnt(0)
; __device__ __forceinline__ void st_bf4(bf16_t* p, f32x4 v) { u32x2 w; w.x = pk2(v[0], v[1]); w.y = pk2(v[2], v[3]); *(u32x2*)p = w; }
; __device__ __forceinline__ float sigmoidf_(float x) { return __builtin_amdgcn_rcpf(1.f + __expf(-x)); }
; __device__ __forceinline__ float dpp_ror1(float v) { return __int_as_float(__builtin_amdgcn_update_dpp(0, __float_as_int(v), 0x121, 0xf, 0xf, false)); }
; __device__ __forceinline__ float dpp_rol1(float v) { return __int_as_float(__builtin_amdgcn_update_dpp(0, __float_as_int(v), 0x12F, 0xf, 0xf, false)); }
;     __device__ __forceinline__ void tile(const f32x4 (&acc)[2][2][4][2], const Unit& u, int wr, int wc, int fr, int fq) const {
;     ...
;                     for (int i = 0; i < 4; ++i) {
;                         const float xv = acc[ai][0][m][n][i], xg = acc[ai][1][m][n][i];
;                         const float uv = m > 0 ? acc[ai][0][m > 0 ? m - 1 : 0][n][i] : 0.f, ug = m > 0 ? acc[ai][1][m > 0 ? m - 1 : 0][n][i] : 0.f;
;                         const float dv = m < 3 ? acc[ai][0][m < 3 ? m + 1 : 3][n][i] : 0.f, dg = m < 3 ? acc[ai][1][m < 3 ? m + 1 : 3][n][i] : 0.f;
;                         const float pv = dpp_ror1(fr == 15 ? uv : xv), pg = dpp_ror1(fr == 15 ? ug : xg);
;                         const float nv = dpp_rol1(fr == 0 ? dv : xv), ng = dpp_rol1(fr == 0 ? dg : xg);
;                         const float yv = wv0[i] * pv + wv1[i] * xv + wv2[i] * nv + bv[i];
;                         const float yg = wg0[i] * pg + wg1[i] * xg + wg2[i] * ng + bg[i];
;                         r[i] = yg * sigmoidf_(yg) * yv;
;                     }
;                     st_bf4(ACT + (size_t)(u.pm * BM + ai * HALF + wr * 64 + m * 16 + fr) * FF + cv, r);
	v_pk_add_f32 v[106:107], v[72:73], v[106:107]
	v_pk_mul_f32 v[108:109], v[108:109], v[124:125]
	v_mov_b32_dpp v123, v126 row_ror:15 row_mask:0xf bank_mask:0xf
	v_pk_mul_f32 v[106:107], v[106:107], v[108:109]
	v_pk_fma_f32 v[108:109], v[78:79], v[118:119], v[114:115]
	v_cvt_pk_bf16_f32 v106, v106, v107
	v_pk_fma_f32 v[108:109], v[82:83], v[122:123], v[108:109]
	v_pk_mul_f32 v[126:127], v[62:63], v[90:91]
	v_pk_add_f32 v[108:109], v[86:87], v[108:109]
	v_pk_fma_f32 v[114:115], v[66:67], v[116:117], v[126:127]
	v_mul_f32_e32 v110, 0xbfb8aa3b, v108
	v_exp_f32_e32 v110, v110
	v_mul_f32_e32 v111, 0xbfb8aa3b, v109
	v_exp_f32_e32 v111, v111
	v_pk_fma_f32 v[114:115], v[70:71], v[120:121], v[114:115]
	v_add_f32_e32 v107, 1.0, v110
	v_rcp_f32_e32 v110, v107
	v_add_f32_e32 v107, 1.0, v111
	v_rcp_f32_e32 v111, v107
	v_pk_add_f32 v[114:115], v[74:75], v[114:115]
	v_pk_mul_f32 v[116:117], v[48:49], v[92:93]
	v_cndmask_b32_e64 v118, v51, v43, s[6:7]
	v_pk_mul_f32 v[108:109], v[108:109], v[110:111]
	v_cndmask_b32_e64 v110, v49, v41, s[6:7]
	v_pk_mul_f32 v[108:109], v[114:115], v[108:109]
	v_cndmask_b32_e64 v111, v54, v46, s[6:7]
	v_cvt_pk_bf16_f32 v107, v108, v109
	global_store_dwordx2 v[168:169], v[106:107], off offset:32
	v_cndmask_b32_e64 v106, v52, v60, s[4:5]
	v_cndmask_b32_e64 v107, v52, v44, s[6:7]
	s_nop 0
	v_mov_b32_dpp v60, v106 row_ror:1 row_mask:0xf bank_mask:0xf
	v_cndmask_b32_e64 v106, v48, v56, s[4:5]
	v_cndmask_b32_e64 v109, v53, v45, s[6:7]
	s_nop 0
	v_mov_b32_dpp v56, v106 row_ror:1 row_mask:0xf bank_mask:0xf
	v_cndmask_b32_e64 v115, v55, v47, s[6:7]
	v_pk_mul_f32 v[120:121], v[52:53], v[88:89]
	v_mov_b32_dpp v106, v107 row_ror:15 row_mask:0xf bank_mask:0xf
	v_cndmask_b32_e64 v107, v48, v40, s[6:7]
	s_nop 1
	v_mov_b32_dpp v108, v107 row_ror:15 row_mask:0xf bank_mask:0xf
	v_cndmask_b32_e64 v107, v53, v61, s[4:5]
	s_nop 1
	v_mov_b32_dpp v61, v107 row_ror:1 row_mask:0xf bank_mask:0xf
	v_cndmask_b32_e64 v107, v49, v57, s[4:5]
	v_pk_fma_f32 v[60:61], v[64:65], v[60:61], v[120:121]
	s_nop 0
	v_mov_b32_dpp v57, v107 row_ror:1 row_mask:0xf bank_mask:0xf
	v_pk_fma_f32 v[56:57], v[76:77], v[56:57], v[116:117]
	s_nop 0
	v_mov_b32_dpp v107, v109 row_ror:15 row_mask:0xf bank_mask:0xf
	v_pk_fma_f32 v[60:61], v[68:69], v[106:107], v[60:61]
	v_pk_mul_f32 v[106:107], v[40:41], v[92:93]
	v_mov_b32_dpp v109, v110 row_ror:15 row_mask:0xf bank_mask:0xf
	v_pk_fma_f32 v[56:57], v[80:81], v[108:109], v[56:57]
	v_cndmask_b32_e64 v110, v54, v62, s[4:5]
	v_pk_add_f32 v[56:57], v[84:85], v[56:57]
	s_nop 0
	v_mul_f32_e32 v108, 0xbfb8aa3b, v56
	v_mul_f32_e32 v117, 0xbfb8aa3b, v57
	v_mov_b32_dpp v62, v110 row_ror:1 row_mask:0xf bank_mask:0xf
	v_cndmask_b32_e64 v110, v50, v58, s[4:5]
	v_exp_f32_e32 v116, v108
	v_exp_f32_e32 v117, v117
	v_mov_b32_dpp v58, v110 row_ror:1 row_mask:0xf bank_mask:0xf
	v_add_f32_e32 v116, 1.0, v116
	v_add_f32_e32 v117, 1.0, v117
	v_mov_b32_dpp v110, v111 row_ror:15 row_mask:0xf bank_mask:0xf
	v_cndmask_b32_e64 v111, v50, v42, s[6:7]
	v_rcp_f32_e32 v116, v116
	v_rcp_f32_e32 v117, v117
	v_mov_b32_dpp v114, v111 row_ror:15 row_mask:0xf bank_mask:0xf
	v_cndmask_b32_e64 v111, v55, v63, s[4:5]
	v_pk_mul_f32 v[108:109], v[50:51], v[94:95]
	v_pk_add_f32 v[60:61], v[72:73], v[60:61]
	v_mov_b32_dpp v63, v111 row_ror:1 row_mask:0xf bank_mask:0xf
	v_cndmask_b32_e64 v111, v51, v59, s[4:5]
	v_pk_mul_f32 v[56:57], v[56:57], v[116:117]
	s_nop 0
	v_mov_b32_dpp v59, v111 row_ror:1 row_mask:0xf bank_mask:0xf
	v_pk_fma_f32 v[58:59], v[78:79], v[58:59], v[108:109]
	v_pk_mul_f32 v[56:57], v[60:61], v[56:57]
	v_mov_b32_dpp v111, v115 row_ror:15 row_mask:0xf bank_mask:0xf
	v_cvt_pk_bf16_f32 v56, v56, v57
	v_cndmask_b32_e64 v108, v43, v35, s[6:7]
	v_mov_b32_dpp v115, v118 row_ror:15 row_mask:0xf bank_mask:0xf
	v_pk_fma_f32 v[58:59], v[82:83], v[114:115], v[58:59]
	v_pk_mul_f32 v[118:119], v[54:55], v[90:91]
	v_pk_add_f32 v[58:59], v[86:87], v[58:59]
	v_pk_fma_f32 v[62:63], v[66:67], v[62:63], v[118:119]
	v_mul_f32_e32 v60, 0xbfb8aa3b, v58
	v_exp_f32_e32 v60, v60
	v_mul_f32_e32 v61, 0xbfb8aa3b, v59
	v_exp_f32_e32 v61, v61
	v_pk_fma_f32 v[62:63], v[70:71], v[110:111], v[62:63]
	v_add_f32_e32 v57, 1.0, v60
	v_rcp_f32_e32 v60, v57
	v_add_f32_e32 v57, 1.0, v61
	v_rcp_f32_e32 v61, v57
	v_pk_add_f32 v[62:63], v[74:75], v[62:63]
	v_pk_mul_f32 v[110:111], v[44:45], v[88:89]
	v_pk_mul_f32 v[58:59], v[58:59], v[60:61]
	s_nop 0
	v_pk_mul_f32 v[58:59], v[62:63], v[58:59]
	v_cndmask_b32_e64 v60, v41, v33, s[6:7]
	v_cvt_pk_bf16_f32 v57, v58, v59
	global_store_dwordx2 v[152:153], v[56:57], off offset:32
	v_cndmask_b32_e64 v56, v44, v52, s[4:5]
	v_cndmask_b32_e64 v57, v44, v36, s[6:7]
	s_nop 0
	v_mov_b32_dpp v52, v56 row_ror:1 row_mask:0xf bank_mask:0xf
	v_cndmask_b32_e64 v56, v40, v48, s[4:5]
	v_cndmask_b32_e64 v59, v45, v37, s[6:7]
	v_cndmask_b32_e64 v61, v46, v38, s[6:7]
	v_mov_b32_dpp v48, v56 row_ror:1 row_mask:0xf bank_mask:0xf
	v_cndmask_b32_e64 v63, v47, v39, s[6:7]
	v_mov_b32_dpp v56, v57 row_ror:15 row_mask:0xf bank_mask:0xf
	v_cndmask_b32_e64 v57, v40, v32, s[6:7]
	s_nop 1
	v_mov_b32_dpp v58, v57 row_ror:15 row_mask:0xf bank_mask:0xf
	v_cndmask_b32_e64 v57, v45, v53, s[4:5]
	s_nop 1
	v_mov_b32_dpp v53, v57 row_ror:1 row_mask:0xf bank_mask:0xf
	v_cndmask_b32_e64 v57, v41, v49, s[4:5]
	v_pk_fma_f32 v[52:53], v[64:65], v[52:53], v[110:111]
	s_nop 0
	v_mov_b32_dpp v49, v57 row_ror:1 row_mask:0xf bank_mask:0xf
	v_pk_fma_f32 v[48:49], v[76:77], v[48:49], v[106:107]
	s_nop 0
	v_mov_b32_dpp v57, v59 row_ror:15 row_mask:0xf bank_mask:0xf
	v_pk_fma_f32 v[52:53], v[68:69], v[56:57], v[52:53]
	v_cndmask_b32_e64 v56, v35, 0, s[6:7]
	v_mov_b32_dpp v59, v60 row_ror:15 row_mask:0xf bank_mask:0xf
; __device__ __forceinline__ void st_bf4(bf16_t* p, f32x4 v) { u32x2 w; w.x = pk2(v[0], v[1]); w.y = pk2(v[2], v[3]); *(u32x2*)p = w; }
; __device__ __forceinline__ float sigmoidf_(float x) { return __builtin_amdgcn_rcpf(1.f + __expf(-x)); }
; __device__ __forceinline__ float dpp_ror1(float v) { return __int_as_float(__builtin_amdgcn_update_dpp(0, __float_as_int(v), 0x121, 0xf, 0xf, false)); }
; __device__ __forceinline__ float dpp_rol1(float v) { return __int_as_float(__builtin_amdgcn_update_dpp(0, __float_as_int(v), 0x12F, 0xf, 0xf, false)); }
;     __device__ __forceinline__ void tile(const f32x4 (&acc)[2][2][4][2], const Unit& u, int wr, int wc, int fr, int fq) const {
;     ...
;                     for (int i = 0; i < 4; ++i) {
;                         const float xv = acc[ai][0][m][n][i], xg = acc[ai][1][m][n][i];
;                         const float uv = m > 0 ? acc[ai][0][m > 0 ? m - 1 : 0][n][i] : 0.f, ug = m > 0 ? acc[ai][1][m > 0 ? m - 1 : 0][n][i] : 0.f;
;                         const float dv = m < 3 ? acc[ai][0][m < 3 ? m + 1 : 3][n][i] : 0.f, dg = m < 3 ? acc[ai][1][m < 3 ? m + 1 : 3][n][i] : 0.f;
;                         const float pv = dpp_ror1(fr == 15 ? uv : xv), pg = dpp_ror1(fr == 15 ? ug : xg);
;                         const float nv = dpp_rol1(fr == 0 ? dv : xv), ng = dpp_rol1(fr == 0 ? dg : xg);
;                         const float yv = wv0[i] * pv + wv1[i] * xv + wv2[i] * nv + bv[i];
;                         const float yg = wg0[i] * pg + wg1[i] * xg + wg2[i] * ng + bg[i];
;                         r[i] = yg * sigmoidf_(yg) * yv;
;                     }
;                     st_bf4(ACT + (size_t)(u.pm * BM + ai * HALF + wr * 64 + m * 16 + fr) * FF + cv, r);
	v_pk_fma_f32 v[48:49], v[80:81], v[58:59], v[48:49]
	v_cndmask_b32_e64 v60, v46, v54, s[4:5]
	v_pk_add_f32 v[48:49], v[84:85], v[48:49]
	s_nop 0
	v_mul_f32_e32 v58, 0xbfb8aa3b, v48
	v_mul_f32_e32 v107, 0xbfb8aa3b, v49
	v_mov_b32_dpp v54, v60 row_ror:1 row_mask:0xf bank_mask:0xf
	v_cndmask_b32_e64 v60, v42, v50, s[4:5]
	v_exp_f32_e32 v106, v58
	v_exp_f32_e32 v107, v107
	v_mov_b32_dpp v50, v60 row_ror:1 row_mask:0xf bank_mask:0xf
	v_add_f32_e32 v106, 1.0, v106
	v_add_f32_e32 v107, 1.0, v107
	v_mov_b32_dpp v60, v61 row_ror:15 row_mask:0xf bank_mask:0xf
	v_cndmask_b32_e64 v61, v42, v34, s[6:7]
	v_rcp_f32_e32 v106, v106
	v_rcp_f32_e32 v107, v107
	v_mov_b32_dpp v62, v61 row_ror:15 row_mask:0xf bank_mask:0xf
	v_cndmask_b32_e64 v61, v47, v55, s[4:5]
	v_pk_mul_f32 v[58:59], v[42:43], v[94:95]
	v_pk_add_f32 v[52:53], v[72:73], v[52:53]
	v_mov_b32_dpp v55, v61 row_ror:1 row_mask:0xf bank_mask:0xf
	v_cndmask_b32_e64 v61, v43, v51, s[4:5]
	v_pk_mul_f32 v[48:49], v[48:49], v[106:107]
	s_nop 0
	v_mov_b32_dpp v51, v61 row_ror:1 row_mask:0xf bank_mask:0xf
	v_pk_fma_f32 v[50:51], v[78:79], v[50:51], v[58:59]
	v_pk_mul_f32 v[48:49], v[52:53], v[48:49]
	v_mov_b32_dpp v61, v63 row_ror:15 row_mask:0xf bank_mask:0xf
	v_cvt_pk_bf16_f32 v48, v48, v49
	s_nop 0
	v_mov_b32_dpp v63, v108 row_ror:15 row_mask:0xf bank_mask:0xf
	v_pk_fma_f32 v[50:51], v[82:83], v[62:63], v[50:51]
	v_pk_mul_f32 v[108:109], v[46:47], v[90:91]
	v_pk_add_f32 v[50:51], v[86:87], v[50:51]
	v_pk_fma_f32 v[54:55], v[66:67], v[54:55], v[108:109]
	v_mul_f32_e32 v52, 0xbfb8aa3b, v50
	v_exp_f32_e32 v52, v52
	v_mul_f32_e32 v53, 0xbfb8aa3b, v51
	v_exp_f32_e32 v53, v53
	v_pk_fma_f32 v[54:55], v[70:71], v[60:61], v[54:55]
	v_add_f32_e32 v49, 1.0, v52
	v_rcp_f32_e32 v52, v49
	v_add_f32_e32 v49, 1.0, v53
	v_rcp_f32_e32 v53, v49
	v_pk_add_f32 v[54:55], v[74:75], v[54:55]
	v_pk_mul_f32 v[50:51], v[50:51], v[52:53]
	s_nop 0
	v_pk_mul_f32 v[50:51], v[54:55], v[50:51]
	v_cndmask_b32_e64 v52, v33, 0, s[6:7]
	v_cvt_pk_bf16_f32 v49, v50, v51
	global_store_dwordx2 v[112:113], v[48:49], off offset:32
	v_cndmask_b32_e64 v48, v36, v44, s[4:5]
	v_cndmask_b32_e64 v49, v36, 0, s[6:7]
	s_nop 0
	v_mov_b32_dpp v44, v48 row_ror:1 row_mask:0xf bank_mask:0xf
	v_cndmask_b32_e64 v48, v32, v40, s[4:5]
	v_cndmask_b32_e64 v51, v37, 0, s[6:7]
	v_cndmask_b32_e64 v53, v38, 0, s[6:7]
	v_mov_b32_dpp v40, v48 row_ror:1 row_mask:0xf bank_mask:0xf
	v_cndmask_b32_e64 v55, v39, 0, s[6:7]
	v_mov_b32_dpp v48, v49 row_ror:15 row_mask:0xf bank_mask:0xf
	v_cndmask_b32_e64 v49, v32, 0, s[6:7]
	s_nop 1
	v_mov_b32_dpp v50, v49 row_ror:15 row_mask:0xf bank_mask:0xf
	v_cndmask_b32_e64 v49, v37, v45, s[4:5]
	v_pk_mul_f32 v[36:37], v[36:37], v[88:89]
	s_nop 0
	v_mov_b32_dpp v45, v49 row_ror:1 row_mask:0xf bank_mask:0xf
	v_cndmask_b32_e64 v49, v33, v41, s[4:5]
	v_pk_mul_f32 v[32:33], v[32:33], v[92:93]
	v_pk_fma_f32 v[36:37], v[64:65], v[44:45], v[36:37]
	v_mov_b32_dpp v41, v49 row_ror:1 row_mask:0xf bank_mask:0xf
	v_pk_fma_f32 v[32:33], v[76:77], v[40:41], v[32:33]
	v_mov_b32_dpp v49, v51 row_ror:15 row_mask:0xf bank_mask:0xf
	v_pk_fma_f32 v[36:37], v[68:69], v[48:49], v[36:37]
	v_pk_mul_f32 v[48:49], v[24:25], v[92:93]
	v_mov_b32_dpp v51, v52 row_ror:15 row_mask:0xf bank_mask:0xf
	v_pk_fma_f32 v[32:33], v[80:81], v[50:51], v[32:33]
	v_cndmask_b32_e64 v52, v38, v46, s[4:5]
	v_pk_add_f32 v[32:33], v[84:85], v[32:33]
	s_nop 0
	v_mul_f32_e32 v40, 0xbfb8aa3b, v32
	v_mul_f32_e32 v41, 0xbfb8aa3b, v33
	v_mov_b32_dpp v46, v52 row_ror:1 row_mask:0xf bank_mask:0xf
	v_cndmask_b32_e64 v52, v34, v42, s[4:5]
	v_exp_f32_e32 v40, v40
	v_exp_f32_e32 v41, v41
	v_mov_b32_dpp v42, v52 row_ror:1 row_mask:0xf bank_mask:0xf
	v_add_f32_e32 v40, 1.0, v40
	v_add_f32_e32 v41, 1.0, v41
	v_mov_b32_dpp v52, v53 row_ror:15 row_mask:0xf bank_mask:0xf
	v_cndmask_b32_e64 v53, v34, 0, s[6:7]
	v_rcp_f32_e32 v40, v40
	v_rcp_f32_e32 v41, v41
	v_mov_b32_dpp v54, v53 row_ror:15 row_mask:0xf bank_mask:0xf
	v_cndmask_b32_e64 v53, v39, v47, s[4:5]
	v_pk_add_f32 v[36:37], v[72:73], v[36:37]
	v_pk_mul_f32 v[32:33], v[32:33], v[40:41]
	v_mov_b32_dpp v47, v53 row_ror:1 row_mask:0xf bank_mask:0xf
	v_cndmask_b32_e64 v53, v35, v43, s[4:5]
	v_pk_mul_f32 v[34:35], v[34:35], v[94:95]
	v_pk_mul_f32 v[32:33], v[36:37], v[32:33]
	v_mov_b32_dpp v43, v53 row_ror:1 row_mask:0xf bank_mask:0xf
	v_pk_fma_f32 v[34:35], v[78:79], v[42:43], v[34:35]
	v_cvt_pk_bf16_f32 v32, v32, v33
	v_mov_b32_dpp v53, v55 row_ror:15 row_mask:0xf bank_mask:0xf
	v_pk_mul_f32 v[38:39], v[38:39], v[90:91]
	v_cndmask_b32_e64 v40, v25, v17, s[6:7]
	v_mov_b32_dpp v55, v56 row_ror:15 row_mask:0xf bank_mask:0xf
	v_pk_fma_f32 v[34:35], v[82:83], v[54:55], v[34:35]
	v_pk_fma_f32 v[38:39], v[66:67], v[46:47], v[38:39]
	v_pk_add_f32 v[34:35], v[86:87], v[34:35]
	v_pk_fma_f32 v[38:39], v[70:71], v[52:53], v[38:39]
	v_mul_f32_e32 v36, 0xbfb8aa3b, v34
	v_exp_f32_e32 v36, v36
	v_mul_f32_e32 v37, 0xbfb8aa3b, v35
	v_exp_f32_e32 v37, v37
	v_pk_add_f32 v[38:39], v[74:75], v[38:39]
	v_add_f32_e32 v33, 1.0, v36
	v_rcp_f32_e32 v36, v33
	v_add_f32_e32 v33, 1.0, v37
	v_rcp_f32_e32 v37, v33
	v_cndmask_b32_e64 v41, v30, 0, s[4:5]
	v_pk_mul_f32 v[34:35], v[34:35], v[36:37]
	s_nop 0
	v_pk_mul_f32 v[34:35], v[38:39], v[34:35]
	s_nop 0
	v_cvt_pk_bf16_f32 v33, v34, v35
	global_store_dwordx2 v[96:97], v[32:33], off offset:32
	v_cndmask_b32_e64 v33, v28, 0, s[4:5]
	v_cndmask_b32_e64 v35, v29, 0, s[4:5]
	s_nop 0
	v_mov_b32_dpp v32, v33 row_ror:1 row_mask:0xf bank_mask:0xf
	v_cndmask_b32_e64 v33, v24, 0, s[4:5]
	v_cndmask_b32_e64 v37, v25, 0, s[4:5]
	v_cndmask_b32_e64 v39, v29, v21, s[6:7]
	v_mov_b32_dpp v34, v33 row_ror:1 row_mask:0xf bank_mask:0xf
; __device__ __forceinline__ void st_bf4(bf16_t* p, f32x4 v) { u32x2 w; w.x = pk2(v[0], v[1]); w.y = pk2(v[2], v[3]); *(u32x2*)p = w; }
; __device__ __forceinline__ float sigmoidf_(float x) { return __builtin_amdgcn_rcpf(1.f + __expf(-x)); }
; __device__ __forceinline__ float dpp_ror1(float v) { return __int_as_float(__builtin_amdgcn_update_dpp(0, __float_as_int(v), 0x121, 0xf, 0xf, false)); }
; __device__ __forceinline__ float dpp_rol1(float v) { return __int_as_float(__builtin_amdgcn_update_dpp(0, __float_as_int(v), 0x12F, 0xf, 0xf, false)); }
;     __device__ __forceinline__ void tile(const f32x4 (&acc)[2][2][4][2], const Unit& u, int wr, int wc, int fr, int fq) const {
;     ...
;                     for (int i = 0; i < 4; ++i) {
;                         const float xv = acc[ai][0][m][n][i], xg = acc[ai][1][m][n][i];
;                         const float uv = m > 0 ? acc[ai][0][m > 0 ? m - 1 : 0][n][i] : 0.f, ug = m > 0 ? acc[ai][1][m > 0 ? m - 1 : 0][n][i] : 0.f;
;                         const float dv = m < 3 ? acc[ai][0][m < 3 ? m + 1 : 3][n][i] : 0.f, dg = m < 3 ? acc[ai][1][m < 3 ? m + 1 : 3][n][i] : 0.f;
;                         const float pv = dpp_ror1(fr == 15 ? uv : xv), pg = dpp_ror1(fr == 15 ? ug : xg);
;                         const float nv = dpp_rol1(fr == 0 ? dv : xv), ng = dpp_rol1(fr == 0 ? dg : xg);
;                         const float yv = wv0[i] * pv + wv1[i] * xv + wv2[i] * nv + bv[i];
;                         const float yg = wg0[i] * pg + wg1[i] * xg + wg2[i] * ng + bg[i];
;                         r[i] = yg * sigmoidf_(yg) * yv;
;                     }
;                     st_bf4(ACT + (size_t)(u.pm * BM + ai * HALF + wr * 64 + m * 16 + fr) * FF + cv, r);
	v_cndmask_b32_e64 v33, v28, v20, s[6:7]
	v_cndmask_b32_e64 v43, v31, 0, s[4:5]
	v_pk_mul_f32 v[52:53], v[28:29], v[88:89]
	v_mov_b32_dpp v36, v33 row_ror:15 row_mask:0xf bank_mask:0xf
	v_cndmask_b32_e64 v33, v24, v16, s[6:7]
	v_cndmask_b32_e64 v45, v27, 0, s[4:5]
	v_cndmask_b32_e64 v47, v31, v23, s[6:7]
	v_mov_b32_dpp v38, v33 row_ror:15 row_mask:0xf bank_mask:0xf
	v_cndmask_b32_e64 v50, v27, v19, s[6:7]
	s_nop 0
	v_mov_b32_dpp v33, v35 row_ror:1 row_mask:0xf bank_mask:0xf
	v_pk_fma_f32 v[32:33], v[64:65], v[32:33], v[52:53]
	s_nop 0
	v_mov_b32_dpp v35, v37 row_ror:1 row_mask:0xf bank_mask:0xf
	v_pk_fma_f32 v[34:35], v[76:77], v[34:35], v[48:49]
	s_nop 0
	v_mov_b32_dpp v37, v39 row_ror:15 row_mask:0xf bank_mask:0xf
	v_pk_fma_f32 v[32:33], v[68:69], v[36:37], v[32:33]
	s_nop 0
	v_mov_b32_dpp v39, v40 row_ror:15 row_mask:0xf bank_mask:0xf
	v_pk_fma_f32 v[34:35], v[80:81], v[38:39], v[34:35]
	s_nop 0
	v_pk_add_f32 v[34:35], v[84:85], v[34:35]
	v_pk_add_f32 v[32:33], v[72:73], v[32:33]
	v_mul_f32_e32 v38, 0xbfb8aa3b, v34
	v_mul_f32_e32 v49, 0xbfb8aa3b, v35
	v_exp_f32_e32 v48, v38
	v_exp_f32_e32 v49, v49
	v_mov_b32_dpp v40, v41 row_ror:1 row_mask:0xf bank_mask:0xf
	v_cndmask_b32_e64 v41, v26, 0, s[4:5]
	v_add_f32_e32 v48, 1.0, v48
	v_add_f32_e32 v49, 1.0, v49
	v_mov_b32_dpp v42, v41 row_ror:1 row_mask:0xf bank_mask:0xf
	v_cndmask_b32_e64 v41, v30, v22, s[6:7]
	v_rcp_f32_e32 v48, v48
	v_rcp_f32_e32 v49, v49
	v_mov_b32_dpp v44, v41 row_ror:15 row_mask:0xf bank_mask:0xf
	v_cndmask_b32_e64 v41, v26, v18, s[6:7]
	v_pk_mul_f32 v[38:39], v[26:27], v[94:95]
	v_pk_mul_f32 v[34:35], v[34:35], v[48:49]
	v_mov_b32_dpp v46, v41 row_ror:15 row_mask:0xf bank_mask:0xf
	v_pk_mul_f32 v[32:33], v[32:33], v[34:35]
	s_nop 0
	v_mov_b32_dpp v41, v43 row_ror:1 row_mask:0xf bank_mask:0xf
	v_cvt_pk_bf16_f32 v32, v32, v33
	s_nop 0
	v_mov_b32_dpp v43, v45 row_ror:1 row_mask:0xf bank_mask:0xf
	v_pk_fma_f32 v[34:35], v[78:79], v[42:43], v[38:39]
	v_cndmask_b32_e64 v42, v19, v11, s[6:7]
	v_mov_b32_dpp v45, v47 row_ror:15 row_mask:0xf bank_mask:0xf
	s_nop 1
	v_mov_b32_dpp v47, v50 row_ror:15 row_mask:0xf bank_mask:0xf
	v_pk_fma_f32 v[34:35], v[82:83], v[46:47], v[34:35]
	v_pk_mul_f32 v[50:51], v[30:31], v[90:91]
	v_pk_add_f32 v[34:35], v[86:87], v[34:35]
	v_pk_fma_f32 v[38:39], v[66:67], v[40:41], v[50:51]
	v_mul_f32_e32 v36, 0xbfb8aa3b, v34
	v_exp_f32_e32 v36, v36
	v_mul_f32_e32 v37, 0xbfb8aa3b, v35
	v_exp_f32_e32 v37, v37
	v_pk_fma_f32 v[38:39], v[70:71], v[44:45], v[38:39]
	v_add_f32_e32 v33, 1.0, v36
	v_rcp_f32_e32 v36, v33
	v_add_f32_e32 v33, 1.0, v37
	v_rcp_f32_e32 v37, v33
	v_pk_add_f32 v[38:39], v[74:75], v[38:39]
	v_pk_mul_f32 v[40:41], v[16:17], v[92:93]
	v_pk_mul_f32 v[44:45], v[20:21], v[88:89]
	v_pk_mul_f32 v[34:35], v[34:35], v[36:37]
	v_cndmask_b32_e64 v36, v17, v9, s[6:7]
	v_pk_mul_f32 v[34:35], v[38:39], v[34:35]
	v_cndmask_b32_e64 v37, v22, v14, s[6:7]
	v_cvt_pk_bf16_f32 v33, v34, v35
	global_store_dwordx2 v[98:99], v[32:33], off offset:32
	v_cndmask_b32_e64 v32, v20, v28, s[4:5]
	v_cndmask_b32_e64 v33, v20, v12, s[6:7]
	s_nop 0
	v_mov_b32_dpp v28, v32 row_ror:1 row_mask:0xf bank_mask:0xf
	v_cndmask_b32_e64 v32, v16, v24, s[4:5]
	v_cndmask_b32_e64 v35, v21, v13, s[6:7]
	s_nop 0
	v_mov_b32_dpp v24, v32 row_ror:1 row_mask:0xf bank_mask:0xf
	v_cndmask_b32_e64 v39, v23, v15, s[6:7]
	s_nop 0
	v_mov_b32_dpp v32, v33 row_ror:15 row_mask:0xf bank_mask:0xf
	v_cndmask_b32_e64 v33, v16, v8, s[6:7]
	s_nop 1
	v_mov_b32_dpp v34, v33 row_ror:15 row_mask:0xf bank_mask:0xf
	v_cndmask_b32_e64 v33, v21, v29, s[4:5]
	s_nop 1
	v_mov_b32_dpp v29, v33 row_ror:1 row_mask:0xf bank_mask:0xf
	v_cndmask_b32_e64 v33, v17, v25, s[4:5]
	v_pk_fma_f32 v[28:29], v[64:65], v[28:29], v[44:45]
	s_nop 0
	v_mov_b32_dpp v25, v33 row_ror:1 row_mask:0xf bank_mask:0xf
	v_pk_fma_f32 v[24:25], v[76:77], v[24:25], v[40:41]
	s_nop 0
	v_mov_b32_dpp v33, v35 row_ror:15 row_mask:0xf bank_mask:0xf
	v_pk_fma_f32 v[28:29], v[68:69], v[32:33], v[28:29]
	v_pk_mul_f32 v[32:33], v[8:9], v[92:93]
	v_mov_b32_dpp v35, v36 row_ror:15 row_mask:0xf bank_mask:0xf
	v_pk_fma_f32 v[24:25], v[80:81], v[34:35], v[24:25]
	v_cndmask_b32_e64 v36, v22, v30, s[4:5]
	v_pk_add_f32 v[24:25], v[84:85], v[24:25]
	s_nop 0
	v_mul_f32_e32 v34, 0xbfb8aa3b, v24
	v_mul_f32_e32 v41, 0xbfb8aa3b, v25
	v_mov_b32_dpp v30, v36 row_ror:1 row_mask:0xf bank_mask:0xf
	v_cndmask_b32_e64 v36, v18, v26, s[4:5]
	v_exp_f32_e32 v40, v34
	v_exp_f32_e32 v41, v41
	v_mov_b32_dpp v26, v36 row_ror:1 row_mask:0xf bank_mask:0xf
	v_add_f32_e32 v40, 1.0, v40
	v_add_f32_e32 v41, 1.0, v41
	v_mov_b32_dpp v36, v37 row_ror:15 row_mask:0xf bank_mask:0xf
	v_cndmask_b32_e64 v37, v18, v10, s[6:7]
	v_rcp_f32_e32 v40, v40
	v_rcp_f32_e32 v41, v41
	v_mov_b32_dpp v38, v37 row_ror:15 row_mask:0xf bank_mask:0xf
	v_cndmask_b32_e64 v37, v23, v31, s[4:5]
	v_pk_mul_f32 v[34:35], v[18:19], v[94:95]
	v_pk_add_f32 v[28:29], v[72:73], v[28:29]
	v_mov_b32_dpp v31, v37 row_ror:1 row_mask:0xf bank_mask:0xf
	v_cndmask_b32_e64 v37, v19, v27, s[4:5]
	v_pk_mul_f32 v[24:25], v[24:25], v[40:41]
	s_nop 0
	v_mov_b32_dpp v27, v37 row_ror:1 row_mask:0xf bank_mask:0xf
	v_pk_fma_f32 v[26:27], v[78:79], v[26:27], v[34:35]
	v_pk_mul_f32 v[24:25], v[28:29], v[24:25]
	v_mov_b32_dpp v37, v39 row_ror:15 row_mask:0xf bank_mask:0xf
	v_cvt_pk_bf16_f32 v24, v24, v25
	v_cndmask_b32_e64 v34, v11, v3, s[6:7]
	v_mov_b32_dpp v39, v42 row_ror:15 row_mask:0xf bank_mask:0xf
	v_pk_fma_f32 v[26:27], v[82:83], v[38:39], v[26:27]
	v_pk_mul_f32 v[42:43], v[22:23], v[90:91]
	v_pk_add_f32 v[26:27], v[86:87], v[26:27]
	v_pk_fma_f32 v[30:31], v[66:67], v[30:31], v[42:43]
	v_mul_f32_e32 v28, 0xbfb8aa3b, v26
	v_exp_f32_e32 v28, v28
; __device__ __forceinline__ void st_bf4(bf16_t* p, f32x4 v) { u32x2 w; w.x = pk2(v[0], v[1]); w.y = pk2(v[2], v[3]); *(u32x2*)p = w; }
; __device__ __forceinline__ float sigmoidf_(float x) { return __builtin_amdgcn_rcpf(1.f + __expf(-x)); }
; __device__ __forceinline__ float dpp_ror1(float v) { return __int_as_float(__builtin_amdgcn_update_dpp(0, __float_as_int(v), 0x121, 0xf, 0xf, false)); }
; __device__ __forceinline__ float dpp_rol1(float v) { return __int_as_float(__builtin_amdgcn_update_dpp(0, __float_as_int(v), 0x12F, 0xf, 0xf, false)); }
; #define PG8_BAR __builtin_amdgcn_s_barrier()
;     __device__ __forceinline__ void tile(const f32x4 (&acc)[2][2][4][2], const Unit& u, int wr, int wc, int fr, int fq) const {
;     ...
;                     for (int i = 0; i < 4; ++i) {
;                         const float xv = acc[ai][0][m][n][i], xg = acc[ai][1][m][n][i];
;                         const float uv = m > 0 ? acc[ai][0][m > 0 ? m - 1 : 0][n][i] : 0.f, ug = m > 0 ? acc[ai][1][m > 0 ? m - 1 : 0][n][i] : 0.f;
;                         const float dv = m < 3 ? acc[ai][0][m < 3 ? m + 1 : 3][n][i] : 0.f, dg = m < 3 ? acc[ai][1][m < 3 ? m + 1 : 3][n][i] : 0.f;
;                         const float pv = dpp_ror1(fr == 15 ? uv : xv), pg = dpp_ror1(fr == 15 ? ug : xg);
;                         const float nv = dpp_rol1(fr == 0 ? dv : xv), ng = dpp_rol1(fr == 0 ? dg : xg);
;                         const float yv = wv0[i] * pv + wv1[i] * xv + wv2[i] * nv + bv[i];
;                         const float yg = wg0[i] * pg + wg1[i] * xg + wg2[i] * ng + bg[i];
;                         r[i] = yg * sigmoidf_(yg) * yv;
;                     }
;                     st_bf4(ACT + (size_t)(u.pm * BM + ai * HALF + wr * 64 + m * 16 + fr) * FF + cv, r);
; template <class Epi, class Sched, bool DEFER>
; __device__ __forceinline__ void gemm_fast_core(LAS unsigned char* lds, const GemmP g, const Sched& S, const Epi& E, f32x4 (&acc)[2][2][4][2], Unit& cur) {
;     ...
;         if (!has_next) break;
; #pragma unroll
;         for (int a = 0; a < 2; ++a)
; #pragma unroll
;             for (int b = 0; b < 2; ++b)
; #pragma unroll
;                 for (int m = 0; m < 4; ++m)
; #pragma unroll
;                     for (int n = 0; n < 2; ++n) acc[a][b][m][n] = (f32x4){0.f, 0.f, 0.f, 0.f};
;         cur = nxt; cA = nA; cB = nB; ++ui;
;         if (wr == 1) PG8_BAR;
;     }
	v_mul_f32_e32 v29, 0xbfb8aa3b, v27
	v_exp_f32_e32 v29, v29
	v_pk_fma_f32 v[30:31], v[70:71], v[36:37], v[30:31]
	v_add_f32_e32 v25, 1.0, v28
	v_rcp_f32_e32 v28, v25
	v_add_f32_e32 v25, 1.0, v29
	v_rcp_f32_e32 v29, v25
	v_pk_add_f32 v[30:31], v[74:75], v[30:31]
	v_pk_mul_f32 v[36:37], v[12:13], v[88:89]
	v_pk_mul_f32 v[26:27], v[26:27], v[28:29]
	s_nop 0
	v_pk_mul_f32 v[26:27], v[30:31], v[26:27]
	v_cndmask_b32_e64 v28, v9, v1, s[6:7]
	v_cvt_pk_bf16_f32 v25, v26, v27
	global_store_dwordx2 v[100:101], v[24:25], off offset:32
	v_cndmask_b32_e64 v24, v12, v20, s[4:5]
	v_cndmask_b32_e64 v25, v12, v4, s[6:7]
	s_nop 0
	v_mov_b32_dpp v20, v24 row_ror:1 row_mask:0xf bank_mask:0xf
	v_cndmask_b32_e64 v24, v8, v16, s[4:5]
	v_cndmask_b32_e64 v27, v13, v5, s[6:7]
	v_cndmask_b32_e64 v29, v14, v6, s[6:7]
	v_mov_b32_dpp v16, v24 row_ror:1 row_mask:0xf bank_mask:0xf
	v_cndmask_b32_e64 v31, v15, v7, s[6:7]
	v_mov_b32_dpp v24, v25 row_ror:15 row_mask:0xf bank_mask:0xf
	v_cndmask_b32_e64 v25, v8, v0, s[6:7]
	s_nop 1
	v_mov_b32_dpp v26, v25 row_ror:15 row_mask:0xf bank_mask:0xf
	v_cndmask_b32_e64 v25, v13, v21, s[4:5]
	s_nop 1
	v_mov_b32_dpp v21, v25 row_ror:1 row_mask:0xf bank_mask:0xf
	v_cndmask_b32_e64 v25, v9, v17, s[4:5]
	v_pk_fma_f32 v[20:21], v[64:65], v[20:21], v[36:37]
	s_nop 0
	v_mov_b32_dpp v17, v25 row_ror:1 row_mask:0xf bank_mask:0xf
	v_pk_fma_f32 v[16:17], v[76:77], v[16:17], v[32:33]
	s_nop 0
	v_mov_b32_dpp v25, v27 row_ror:15 row_mask:0xf bank_mask:0xf
	v_pk_fma_f32 v[20:21], v[68:69], v[24:25], v[20:21]
	v_cndmask_b32_e64 v24, v3, 0, s[6:7]
	v_mov_b32_dpp v27, v28 row_ror:15 row_mask:0xf bank_mask:0xf
	v_pk_fma_f32 v[16:17], v[80:81], v[26:27], v[16:17]
	v_cndmask_b32_e64 v28, v14, v22, s[4:5]
	v_pk_add_f32 v[16:17], v[84:85], v[16:17]
	s_nop 0
	v_mul_f32_e32 v26, 0xbfb8aa3b, v16
	v_mul_f32_e32 v33, 0xbfb8aa3b, v17
	v_mov_b32_dpp v22, v28 row_ror:1 row_mask:0xf bank_mask:0xf
	v_cndmask_b32_e64 v28, v10, v18, s[4:5]
	v_exp_f32_e32 v32, v26
	v_exp_f32_e32 v33, v33
	v_mov_b32_dpp v18, v28 row_ror:1 row_mask:0xf bank_mask:0xf
	v_add_f32_e32 v32, 1.0, v32
	v_add_f32_e32 v33, 1.0, v33
	v_mov_b32_dpp v28, v29 row_ror:15 row_mask:0xf bank_mask:0xf
	v_cndmask_b32_e64 v29, v10, v2, s[6:7]
	v_rcp_f32_e32 v32, v32
	v_rcp_f32_e32 v33, v33
	v_mov_b32_dpp v30, v29 row_ror:15 row_mask:0xf bank_mask:0xf
	v_cndmask_b32_e64 v29, v15, v23, s[4:5]
	v_pk_mul_f32 v[26:27], v[10:11], v[94:95]
	v_pk_add_f32 v[20:21], v[72:73], v[20:21]
	v_mov_b32_dpp v23, v29 row_ror:1 row_mask:0xf bank_mask:0xf
	v_cndmask_b32_e64 v29, v11, v19, s[4:5]
	v_pk_mul_f32 v[16:17], v[16:17], v[32:33]
	s_nop 0
	v_mov_b32_dpp v19, v29 row_ror:1 row_mask:0xf bank_mask:0xf
	v_pk_fma_f32 v[18:19], v[78:79], v[18:19], v[26:27]
	v_pk_mul_f32 v[16:17], v[20:21], v[16:17]
	v_mov_b32_dpp v29, v31 row_ror:15 row_mask:0xf bank_mask:0xf
	v_cvt_pk_bf16_f32 v16, v16, v17
	s_nop 0
	v_mov_b32_dpp v31, v34 row_ror:15 row_mask:0xf bank_mask:0xf
	v_pk_fma_f32 v[18:19], v[82:83], v[30:31], v[18:19]
	v_pk_mul_f32 v[34:35], v[14:15], v[90:91]
	v_pk_add_f32 v[18:19], v[86:87], v[18:19]
	v_pk_fma_f32 v[22:23], v[66:67], v[22:23], v[34:35]
	v_mul_f32_e32 v20, 0xbfb8aa3b, v18
	v_exp_f32_e32 v20, v20
	v_mul_f32_e32 v21, 0xbfb8aa3b, v19
	v_exp_f32_e32 v21, v21
	v_pk_fma_f32 v[22:23], v[70:71], v[28:29], v[22:23]
	v_add_f32_e32 v17, 1.0, v20
	v_rcp_f32_e32 v20, v17
	v_add_f32_e32 v17, 1.0, v21
	v_rcp_f32_e32 v21, v17
	v_pk_add_f32 v[22:23], v[74:75], v[22:23]
	v_pk_mul_f32 v[18:19], v[18:19], v[20:21]
	s_nop 0
	v_pk_mul_f32 v[18:19], v[22:23], v[18:19]
	v_cndmask_b32_e64 v20, v1, 0, s[6:7]
	v_cvt_pk_bf16_f32 v17, v18, v19
	global_store_dwordx2 v[102:103], v[16:17], off offset:32
	v_cndmask_b32_e64 v16, v4, v12, s[4:5]
	v_cndmask_b32_e64 v17, v4, 0, s[6:7]
	s_nop 0
	v_mov_b32_dpp v12, v16 row_ror:1 row_mask:0xf bank_mask:0xf
	v_cndmask_b32_e64 v16, v0, v8, s[4:5]
	v_cndmask_b32_e64 v19, v5, 0, s[6:7]
	v_cndmask_b32_e64 v21, v6, 0, s[6:7]
	v_mov_b32_dpp v8, v16 row_ror:1 row_mask:0xf bank_mask:0xf
	v_cndmask_b32_e64 v23, v7, 0, s[6:7]
	v_mov_b32_dpp v16, v17 row_ror:15 row_mask:0xf bank_mask:0xf
	v_cndmask_b32_e64 v17, v0, 0, s[6:7]
	s_nop 1
	v_mov_b32_dpp v18, v17 row_ror:15 row_mask:0xf bank_mask:0xf
	v_cndmask_b32_e64 v17, v5, v13, s[4:5]
	v_pk_mul_f32 v[4:5], v[4:5], v[88:89]
	s_nop 0
	v_mov_b32_dpp v13, v17 row_ror:1 row_mask:0xf bank_mask:0xf
	v_cndmask_b32_e64 v17, v1, v9, s[4:5]
	v_pk_mul_f32 v[0:1], v[0:1], v[92:93]
	v_pk_fma_f32 v[4:5], v[64:65], v[12:13], v[4:5]
	v_mov_b32_dpp v9, v17 row_ror:1 row_mask:0xf bank_mask:0xf
	v_pk_fma_f32 v[0:1], v[76:77], v[8:9], v[0:1]
	s_nop 0
	v_mov_b32_dpp v17, v19 row_ror:15 row_mask:0xf bank_mask:0xf
	v_pk_fma_f32 v[4:5], v[68:69], v[16:17], v[4:5]
	s_nop 0
	v_mov_b32_dpp v19, v20 row_ror:15 row_mask:0xf bank_mask:0xf
	v_pk_fma_f32 v[0:1], v[80:81], v[18:19], v[0:1]
	v_cndmask_b32_e64 v20, v6, v14, s[4:5]
	v_pk_add_f32 v[0:1], v[84:85], v[0:1]
	s_nop 0
	v_mul_f32_e32 v8, 0xbfb8aa3b, v1
	v_exp_f32_e32 v8, v8
	v_mul_f32_e32 v9, 0xbfb8aa3b, v0
	v_mov_b32_dpp v14, v20 row_ror:1 row_mask:0xf bank_mask:0xf
	v_cndmask_b32_e64 v20, v2, v10, s[4:5]
	v_exp_f32_e32 v18, v9
	v_add_f32_e32 v8, 1.0, v8
	v_mov_b32_dpp v10, v20 row_ror:1 row_mask:0xf bank_mask:0xf
	v_rcp_f32_e32 v9, v8
	v_add_f32_e32 v8, 1.0, v18
	v_mov_b32_dpp v20, v21 row_ror:15 row_mask:0xf bank_mask:0xf
	v_cndmask_b32_e64 v21, v2, 0, s[6:7]
	v_rcp_f32_e32 v8, v8
	v_pk_add_f32 v[4:5], v[72:73], v[4:5]
	v_mov_b32_dpp v22, v21 row_ror:15 row_mask:0xf bank_mask:0xf
	v_cndmask_b32_e64 v21, v7, v15, s[4:5]
	v_pk_mul_f32 v[0:1], v[0:1], v[8:9]
	v_pk_mul_f32 v[6:7], v[6:7], v[90:91]
	v_mov_b32_dpp v15, v21 row_ror:1 row_mask:0xf bank_mask:0xf
	v_cndmask_b32_e64 v21, v3, v11, s[4:5]
	v_pk_mul_f32 v[2:3], v[2:3], v[94:95]
	v_pk_mul_f32 v[0:1], v[4:5], v[0:1]
	v_mov_b32_dpp v11, v21 row_ror:1 row_mask:0xf bank_mask:0xf
	v_pk_fma_f32 v[2:3], v[78:79], v[10:11], v[2:3]
	v_cvt_pk_bf16_f32 v0, v0, v1
	v_mov_b32_dpp v21, v23 row_ror:15 row_mask:0xf bank_mask:0xf
	v_pk_fma_f32 v[6:7], v[66:67], v[14:15], v[6:7]
	s_nop 0
	v_mov_b32_dpp v23, v24 row_ror:15 row_mask:0xf bank_mask:0xf
	v_pk_fma_f32 v[2:3], v[82:83], v[22:23], v[2:3]
	v_pk_fma_f32 v[6:7], v[70:71], v[20:21], v[6:7]
	v_pk_add_f32 v[2:3], v[86:87], v[2:3]
	v_pk_add_f32 v[6:7], v[74:75], v[6:7]
	v_mul_f32_e32 v4, 0xbfb8aa3b, v2
	v_exp_f32_e32 v4, v4
	v_mul_f32_e32 v5, 0xbfb8aa3b, v3
	v_exp_f32_e32 v5, v5
	v_add_f32_e32 v1, 1.0, v4
	v_rcp_f32_e32 v4, v1
	v_add_f32_e32 v1, 1.0, v5
	v_rcp_f32_e32 v5, v1
	s_nop 0
	v_pk_mul_f32 v[2:3], v[2:3], v[4:5]
	s_nop 0
	v_pk_mul_f32 v[2:3], v[6:7], v[2:3]
	s_nop 0
	v_cvt_pk_bf16_f32 v1, v2, v3
	global_store_dwordx2 v[104:105], v[0:1], off offset:32
	s_cbranch_vccnz .LBB0_1795
	s_andn2_b64 vcc, exec, s[2:3]
	s_cbranch_vccnz .LBB0_1794
	s_barrier
	s_branch .LBB0_1794

; template <class Epi, class Sched, bool DEFER>
; __device__ __forceinline__ void gemm_fast_core(LAS unsigned char* lds, const GemmP g, const Sched& S, const Epi& E, f32x4 (&acc)[2][2][4][2], Unit& cur) {
;     ...
;         for (int a = 0; a < 2; ++a)
; #pragma unroll
;             for (int b = 0; b < 2; ++b)
; #pragma unroll
;                 for (int m = 0; m < 4; ++m)
; #pragma unroll
;                     for (int n = 0; n < 2; ++n) acc[a][b][m][n] = (f32x4){0.f, 0.f, 0.f, 0.f};
;         cur = nxt; cA = nA; cB = nB; ++ui;
.LBB0_1885:
	s_add_u32 s45, s20, 0x100
	v_mov_b32_e32 v0, 0
	s_addc_u32 s46, s21, 0
	s_mov_b32 s47, -2
	v_mov_b32_e32 v1, v0
	v_mov_b32_e32 v2, v0
	v_mov_b32_e32 v3, v0
	v_mov_b32_e32 v4, v0
	v_mov_b32_e32 v5, v0
	v_mov_b32_e32 v6, v0
	v_mov_b32_e32 v7, v0
	v_mov_b32_e32 v16, v0
	v_mov_b32_e32 v17, v0
	v_mov_b32_e32 v18, v0
	v_mov_b32_e32 v19, v0
	v_mov_b32_e32 v20, v0
	v_mov_b32_e32 v21, v0
	v_mov_b32_e32 v22, v0
	v_mov_b32_e32 v23, v0
	v_mov_b32_e32 v32, v0
	v_mov_b32_e32 v33, v0
	v_mov_b32_e32 v34, v0
	v_mov_b32_e32 v35, v0
	v_mov_b32_e32 v36, v0
	v_mov_b32_e32 v37, v0
	v_mov_b32_e32 v38, v0
	v_mov_b32_e32 v39, v0
	v_mov_b32_e32 v48, v0
	v_mov_b32_e32 v49, v0
	v_mov_b32_e32 v50, v0
	v_mov_b32_e32 v51, v0
	v_mov_b32_e32 v52, v0
	v_mov_b32_e32 v53, v0
	v_mov_b32_e32 v54, v0
	v_mov_b32_e32 v55, v0
	v_mov_b32_e32 v8, v0
	v_mov_b32_e32 v9, v0
	v_mov_b32_e32 v10, v0
	v_mov_b32_e32 v11, v0
	v_mov_b32_e32 v12, v0
	v_mov_b32_e32 v13, v0
	v_mov_b32_e32 v14, v0
	v_mov_b32_e32 v15, v0
	v_mov_b32_e32 v24, v0
	v_mov_b32_e32 v25, v0
	v_mov_b32_e32 v26, v0
	v_mov_b32_e32 v27, v0
	v_mov_b32_e32 v28, v0
	v_mov_b32_e32 v29, v0
	v_mov_b32_e32 v30, v0
	v_mov_b32_e32 v31, v0
	v_mov_b32_e32 v40, v0
	v_mov_b32_e32 v41, v0
	v_mov_b32_e32 v42, v0
	v_mov_b32_e32 v43, v0
	v_mov_b32_e32 v44, v0
	v_mov_b32_e32 v45, v0
	v_mov_b32_e32 v46, v0
	v_mov_b32_e32 v47, v0
	v_mov_b32_e32 v56, v0
	v_mov_b32_e32 v57, v0
	v_mov_b32_e32 v58, v0
	v_mov_b32_e32 v59, v0
	v_mov_b32_e32 v60, v0
	v_mov_b32_e32 v61, v0
	v_mov_b32_e32 v62, v0
	v_mov_b32_e32 v63, v0
	v_mov_b32_e32 v68, v0
	v_mov_b32_e32 v69, v0
	v_mov_b32_e32 v70, v0
	v_mov_b32_e32 v71, v0
	v_mov_b32_e32 v72, v0
	v_mov_b32_e32 v73, v0
	v_mov_b32_e32 v74, v0
	v_mov_b32_e32 v75, v0
	v_mov_b32_e32 v84, v0
	v_mov_b32_e32 v85, v0
	v_mov_b32_e32 v86, v0
	v_mov_b32_e32 v87, v0
	v_mov_b32_e32 v88, v0
	v_mov_b32_e32 v89, v0
	v_mov_b32_e32 v90, v0
	v_mov_b32_e32 v91, v0
	v_mov_b32_e32 v100, v0
	v_mov_b32_e32 v101, v0
	v_mov_b32_e32 v102, v0
	v_mov_b32_e32 v103, v0
	v_mov_b32_e32 v104, v0
	v_mov_b32_e32 v105, v0
	v_mov_b32_e32 v106, v0
	v_mov_b32_e32 v107, v0
	v_mov_b32_e32 v116, v0
	v_mov_b32_e32 v117, v0
	v_mov_b32_e32 v118, v0
	v_mov_b32_e32 v119, v0
	v_mov_b32_e32 v120, v0
	v_mov_b32_e32 v121, v0
	v_mov_b32_e32 v122, v0
	v_mov_b32_e32 v123, v0
	v_mov_b32_e32 v76, v0
	v_mov_b32_e32 v77, v0
	v_mov_b32_e32 v78, v0
	v_mov_b32_e32 v79, v0
	v_mov_b32_e32 v80, v0
	v_mov_b32_e32 v81, v0
	v_mov_b32_e32 v82, v0
	v_mov_b32_e32 v83, v0
	v_mov_b32_e32 v92, v0
	v_mov_b32_e32 v93, v0
	v_mov_b32_e32 v94, v0
	v_mov_b32_e32 v95, v0
	v_mov_b32_e32 v96, v0
	v_mov_b32_e32 v97, v0
	v_mov_b32_e32 v98, v0
	v_mov_b32_e32 v99, v0
	v_mov_b32_e32 v108, v0
	v_mov_b32_e32 v109, v0
	v_mov_b32_e32 v110, v0
	v_mov_b32_e32 v111, v0
	v_mov_b32_e32 v112, v0
	v_mov_b32_e32 v113, v0
	v_mov_b32_e32 v114, v0
	v_mov_b32_e32 v115, v0
	v_mov_b32_e32 v124, v0
	v_mov_b32_e32 v125, v0
	v_mov_b32_e32 v126, v0
	v_mov_b32_e32 v127, v0
	v_mov_b32_e32 v128, v0
	v_mov_b32_e32 v129, v0
	v_mov_b32_e32 v130, v0
	v_mov_b32_e32 v131, v0
	.p2align 6
